# speedup vs baseline: 1.0152x; 1.0055x over previous
;   #define LDA(dst,b,h) for(int m=0;m<4;++m)for(int k=0;k<2;++k) \
;     dst[m][k]=*reinterpret_cast<const bf16x8*>((char*)SA(b,h)+lds_byte(wr*64+m*16+fr,k*32+fq*8))
;   #define LDB(dst,b,h) for(int n=0;n<2;++n)for(int k=0;k<2;++k) \
;     dst[n][k]=*reinterpret_cast<const bf16x8*>((char*)SB(b,h)+lds_byte(wc*32+n*16+fr,k*32+fq*8))
;   #define MMA(ai,bj,At,Bt_) do{__builtin_amdgcn_s_setprio(1); \
;     for(int m=0;m<4;++m)for(int n=0;n<2;++n)for(int k=0;k<2;++k) \
;       acc[ai][bj][m][n]=__builtin_amdgcn_mfma_f32_16x16x32_bf16(Bt_[n][k],At[m][k],acc[ai][bj][m][n],0,0,0); \
;     __builtin_amdgcn_s_setprio(0);}while(0)
;   #define WAIT_V(n) asm volatile("s_waitcnt vmcnt(" #n ")":::"memory")
;   #define WAIT_L(n) asm volatile("s_waitcnt lgkmcnt(" #n ")":::"memory")
;   #define BAR __builtin_amdgcn_s_barrier()
;   #define SCHED __builtin_amdgcn_sched_barrier(0)
; __device__ __forceinline__ void gll16(const void* g, const void* l) {
;   const unsigned m = __builtin_amdgcn_readfirstlane((unsigned)(uintptr_t)l);
;   asm volatile("s_mov_b32 m0, %0\n\tglobal_load_lds_dwordx4 %1, off" :: "s"(m), "v"(g) : "memory");
; }
; template <bool TWO, class MID> ...
;     ...
;     LDB(B0,0,0); SCHED; LDA(At,0,0); STAGE_A(SA(1,1),1,t+1);
;     WAIT_L(8); BAR; WAIT_L(0); MMA(0,0,At,B0); BAR; SCHED;
;     LDB(B1,0,1); STAGE_B(SB(0,0),0,t+2);
;     BAR; WAIT_L(0); MMA(0,1,At,B1); BAR;
;     LDA(At,0,1); STAGE_A(SA(0,0),0,t+2);
;     BAR; WAIT_L(0); MMA(1,0,At,B0); BAR; SCHED;
;     STAGE_B(SB(0,1),1,t+2);
;     WAIT_V(6); BAR; MMA(1,1,At,B1); BAR;
.LBB0_169:
	ds_read_b128 v[170:173], v143
	ds_read_b128 v[174:177], v143 offset:1024
	ds_read_b128 v[178:181], v143 offset:2048
	ds_read_b128 v[182:185], v143 offset:3072
	ds_read_b128 v[186:189], v168
	ds_read_b128 v[190:193], v168 offset:1024
	ds_read_b128 v[196:199], v167
	ds_read_b128 v[200:203], v167 offset:1024
	ds_read_b128 v[204:207], v166
	ds_read_b128 v[208:211], v166 offset:1024
	ds_read_b128 v[212:215], v147
	ds_read_b128 v[216:219], v147 offset:1024
	s_add_u32 s17, s0, s12
	s_addc_u32 s18, s1, s13
	s_add_u32 s20, s17, 0x8080080
	s_addc_u32 s21, s18, 0
	v_readfirstlane_b32 s19, v148
	s_mov_b32 m0, s19
	global_load_lds_dwordx4 v132, s[20:21]
	v_readfirstlane_b32 s19, v156
	s_mov_b32 m0, s19
	global_load_lds_dwordx4 v130, s[20:21]
	s_waitcnt lgkmcnt(8)
	s_barrier
	s_waitcnt lgkmcnt(0)
	s_setprio 1
	v_mfma_f32_16x16x32_bf16 v[126:129], v[170:173], v[186:189], v[126:129]
	v_mfma_f32_16x16x32_bf16 v[122:125], v[178:181], v[186:189], v[122:125]
	v_mfma_f32_16x16x32_bf16 v[118:121], v[170:173], v[196:199], v[118:121]
	v_mfma_f32_16x16x32_bf16 v[114:117], v[178:181], v[196:199], v[114:117]
	v_mfma_f32_16x16x32_bf16 v[110:113], v[170:173], v[204:207], v[110:113]
	v_mfma_f32_16x16x32_bf16 v[106:109], v[178:181], v[204:207], v[106:109]
	v_mfma_f32_16x16x32_bf16 v[102:105], v[170:173], v[212:215], v[102:105]
	v_mfma_f32_16x16x32_bf16 v[98:101], v[178:181], v[212:215], v[98:101]
	v_mfma_f32_16x16x32_bf16 v[126:129], v[174:177], v[190:193], v[126:129]
	v_mfma_f32_16x16x32_bf16 v[122:125], v[182:185], v[190:193], v[122:125]
	v_mfma_f32_16x16x32_bf16 v[118:121], v[174:177], v[200:203], v[118:121]
	v_mfma_f32_16x16x32_bf16 v[114:117], v[182:185], v[200:203], v[114:117]
	v_mfma_f32_16x16x32_bf16 v[110:113], v[174:177], v[208:211], v[110:113]
	v_mfma_f32_16x16x32_bf16 v[106:109], v[182:185], v[208:211], v[106:109]
	v_mfma_f32_16x16x32_bf16 v[102:105], v[174:177], v[216:219], v[102:105]
	v_mfma_f32_16x16x32_bf16 v[98:101], v[182:185], v[216:219], v[98:101]
	s_setprio 0
	s_barrier
	s_add_u32 s19, s0, s14
	ds_read_b128 v[220:223], v141
	ds_read_b128 v[224:227], v141 offset:1024
	ds_read_b128 v[228:231], v141 offset:2048
	ds_read_b128 v[232:235], v141 offset:3072
	s_addc_u32 s20, s1, s15
	s_add_u32 s26, s19, 0x100
	s_addc_u32 s27, s20, 0
	v_readfirstlane_b32 s21, v150
	s_mov_b32 m0, s21
	global_load_lds_dwordx4 v132, s[26:27]
	v_readfirstlane_b32 s21, v158
	s_mov_b32 m0, s21
	global_load_lds_dwordx4 v130, s[26:27]
	s_barrier
	s_waitcnt lgkmcnt(0)
	s_setprio 1
	v_mfma_f32_16x16x32_bf16 v[94:97], v[220:223], v[186:189], v[94:97]
	v_mfma_f32_16x16x32_bf16 v[90:93], v[228:231], v[186:189], v[90:93]
	v_mfma_f32_16x16x32_bf16 v[86:89], v[220:223], v[196:199], v[86:89]
	v_mfma_f32_16x16x32_bf16 v[82:85], v[228:231], v[196:199], v[82:85]
	v_mfma_f32_16x16x32_bf16 v[78:81], v[220:223], v[204:207], v[78:81]
	v_mfma_f32_16x16x32_bf16 v[74:77], v[228:231], v[204:207], v[74:77]
	v_mfma_f32_16x16x32_bf16 v[70:73], v[220:223], v[212:215], v[70:73]
	v_mfma_f32_16x16x32_bf16 v[66:69], v[228:231], v[212:215], v[66:69]
	v_mfma_f32_16x16x32_bf16 v[94:97], v[224:227], v[190:193], v[94:97]
	v_mfma_f32_16x16x32_bf16 v[90:93], v[232:235], v[190:193], v[90:93]
	v_mfma_f32_16x16x32_bf16 v[86:89], v[224:227], v[200:203], v[86:89]
	v_mfma_f32_16x16x32_bf16 v[82:85], v[232:235], v[200:203], v[82:85]
	v_mfma_f32_16x16x32_bf16 v[78:81], v[224:227], v[208:211], v[78:81]
	v_mfma_f32_16x16x32_bf16 v[74:77], v[232:235], v[208:211], v[74:77]
	v_mfma_f32_16x16x32_bf16 v[70:73], v[224:227], v[216:219], v[70:73]
	v_mfma_f32_16x16x32_bf16 v[66:69], v[232:235], v[216:219], v[66:69]
	s_setprio 0
	s_barrier
	ds_read_b128 v[186:189], v168 offset:16384
	ds_read_b128 v[190:193], v168 offset:17408
	ds_read_b128 v[196:199], v167 offset:16384
	ds_read_b128 v[200:203], v167 offset:17408
	ds_read_b128 v[204:207], v166 offset:16384
	ds_read_b128 v[208:211], v166 offset:17408
	ds_read_b128 v[212:215], v147 offset:16384
	ds_read_b128 v[216:219], v147 offset:17408
	s_add_u32 s26, s17, 0x8000100
	s_addc_u32 s27, s18, 0
	v_readfirstlane_b32 s21, v138
	s_mov_b32 m0, s21
	global_load_lds_dwordx4 v132, s[26:27]
	v_readfirstlane_b32 s21, v160
	s_mov_b32 m0, s21
	global_load_lds_dwordx4 v130, s[26:27]
	s_barrier
	s_waitcnt lgkmcnt(0)
	s_setprio 1
	v_mfma_f32_16x16x32_bf16 v[62:65], v[170:173], v[186:189], v[62:65]
	v_mfma_f32_16x16x32_bf16 v[58:61], v[178:181], v[186:189], v[58:61]
	v_mfma_f32_16x16x32_bf16 v[54:57], v[170:173], v[196:199], v[54:57]
	v_mfma_f32_16x16x32_bf16 v[50:53], v[178:181], v[196:199], v[50:53]
	v_mfma_f32_16x16x32_bf16 v[46:49], v[170:173], v[204:207], v[46:49]
	v_mfma_f32_16x16x32_bf16 v[42:45], v[178:181], v[204:207], v[42:45]
	v_mfma_f32_16x16x32_bf16 v[38:41], v[170:173], v[212:215], v[38:41]
	v_mfma_f32_16x16x32_bf16 v[34:37], v[178:181], v[212:215], v[34:37]
	v_mfma_f32_16x16x32_bf16 v[62:65], v[174:177], v[190:193], v[62:65]
	v_mfma_f32_16x16x32_bf16 v[58:61], v[182:185], v[190:193], v[58:61]
	v_mfma_f32_16x16x32_bf16 v[54:57], v[174:177], v[200:203], v[54:57]
	v_mfma_f32_16x16x32_bf16 v[50:53], v[182:185], v[200:203], v[50:53]
	v_mfma_f32_16x16x32_bf16 v[46:49], v[174:177], v[208:211], v[46:49]
	v_mfma_f32_16x16x32_bf16 v[42:45], v[182:185], v[208:211], v[42:45]
	v_mfma_f32_16x16x32_bf16 v[38:41], v[174:177], v[216:219], v[38:41]
	v_mfma_f32_16x16x32_bf16 v[34:37], v[182:185], v[216:219], v[34:37]
	s_setprio 0
	s_barrier
	s_add_u32 s26, s19, 0x80100
	s_addc_u32 s27, s20, 0
	v_readfirstlane_b32 s21, v152
	s_mov_b32 m0, s21
	global_load_lds_dwordx4 v132, s[26:27]
	v_readfirstlane_b32 s21, v162
	s_mov_b32 m0, s21
	global_load_lds_dwordx4 v130, s[26:27]
	s_waitcnt vmcnt(6)
	s_barrier
;   #define LDA(dst,b,h) for(int m=0;m<4;++m)for(int k=0;k<2;++k) \
;     dst[m][k]=*reinterpret_cast<const bf16x8*>((char*)SA(b,h)+lds_byte(wr*64+m*16+fr,k*32+fq*8))
;   #define LDB(dst,b,h) for(int n=0;n<2;++n)for(int k=0;k<2;++k) \
;     dst[n][k]=*reinterpret_cast<const bf16x8*>((char*)SB(b,h)+lds_byte(wc*32+n*16+fr,k*32+fq*8))
;   #define MMA(ai,bj,At,Bt_) do{__builtin_amdgcn_s_setprio(1); \
;     for(int m=0;m<4;++m)for(int n=0;n<2;++n)for(int k=0;k<2;++k) \
;       acc[ai][bj][m][n]=__builtin_amdgcn_mfma_f32_16x16x32_bf16(Bt_[n][k],At[m][k],acc[ai][bj][m][n],0,0,0); \
;     __builtin_amdgcn_s_setprio(0);}while(0)
;   #define WAIT_V(n) asm volatile("s_waitcnt vmcnt(" #n ")":::"memory")
;   #define WAIT_L(n) asm volatile("s_waitcnt lgkmcnt(" #n ")":::"memory")
;   #define BAR __builtin_amdgcn_s_barrier()
;   #define SCHED __builtin_amdgcn_sched_barrier(0)
; __device__ __forceinline__ void gll16(const void* g, const void* l) {
;   const unsigned m = __builtin_amdgcn_readfirstlane((unsigned)(uintptr_t)l);
;   asm volatile("s_mov_b32 m0, %0\n\tglobal_load_lds_dwordx4 %1, off" :: "s"(m), "v"(g) : "memory");
; }
; template <bool TWO, class MID> ...
;     ...
;     WAIT_V(6); BAR; MMA(1,1,At,B1); BAR;
;     LDB(B0,1,0); SCHED; LDA(At,1,0); STAGE_A(SA(0,1),1,t+2);
;     WAIT_L(8); BAR; WAIT_L(0); MMA(0,0,At,B0); BAR; SCHED;
;     LDB(B1,1,1); STAGE_B(SB(1,0),0,t+3);
;     BAR; WAIT_L(0); MMA(0,1,At,B1); BAR;
;     LDA(At,1,1); STAGE_A(SA(1,0),0,t+3);
	s_setprio 1
	v_mfma_f32_16x16x32_bf16 v[30:33], v[220:223], v[186:189], v[30:33]
	v_mfma_f32_16x16x32_bf16 v[26:29], v[228:231], v[186:189], v[26:29]
	v_mfma_f32_16x16x32_bf16 v[22:25], v[220:223], v[196:199], v[22:25]
	v_mfma_f32_16x16x32_bf16 v[18:21], v[228:231], v[196:199], v[18:21]
	v_mfma_f32_16x16x32_bf16 v[14:17], v[220:223], v[204:207], v[14:17]
	v_mfma_f32_16x16x32_bf16 v[10:13], v[228:231], v[204:207], v[10:13]
	v_mfma_f32_16x16x32_bf16 v[6:9], v[220:223], v[212:215], v[6:9]
	v_mfma_f32_16x16x32_bf16 v[2:5], v[228:231], v[212:215], v[2:5]
	v_mfma_f32_16x16x32_bf16 v[30:33], v[224:227], v[190:193], v[30:33]
	v_mfma_f32_16x16x32_bf16 v[26:29], v[232:235], v[190:193], v[26:29]
	v_mfma_f32_16x16x32_bf16 v[22:25], v[224:227], v[200:203], v[22:25]
	v_mfma_f32_16x16x32_bf16 v[18:21], v[232:235], v[200:203], v[18:21]
	v_mfma_f32_16x16x32_bf16 v[14:17], v[224:227], v[208:211], v[14:17]
	v_mfma_f32_16x16x32_bf16 v[10:13], v[232:235], v[208:211], v[10:13]
	v_mfma_f32_16x16x32_bf16 v[6:9], v[224:227], v[216:219], v[6:9]
	v_mfma_f32_16x16x32_bf16 v[2:5], v[232:235], v[216:219], v[2:5]
	s_setprio 0
	s_barrier
	ds_read_b128 v[170:173], v137
	ds_read_b128 v[174:177], v137 offset:1024
	ds_read_b128 v[178:181], v137 offset:2048
	ds_read_b128 v[182:185], v137 offset:3072
	ds_read_b128 v[186:189], v168 offset:32768
	ds_read_b128 v[190:193], v168 offset:33792
	ds_read_b128 v[196:199], v167 offset:32768
	ds_read_b128 v[200:203], v167 offset:33792
	ds_read_b128 v[204:207], v166 offset:32768
	ds_read_b128 v[208:211], v166 offset:33792
	ds_read_b128 v[212:215], v147 offset:32768
	ds_read_b128 v[216:219], v147 offset:33792
	s_add_u32 s26, s17, 0x8080100
	s_addc_u32 s27, s18, 0
	v_readfirstlane_b32 s21, v154
	s_mov_b32 m0, s21
	global_load_lds_dwordx4 v132, s[26:27]
	v_readfirstlane_b32 s21, v164
	s_mov_b32 m0, s21
	global_load_lds_dwordx4 v130, s[26:27]
	s_waitcnt lgkmcnt(8)
	s_barrier
	s_waitcnt lgkmcnt(0)
	s_setprio 1
	v_mfma_f32_16x16x32_bf16 v[126:129], v[170:173], v[186:189], v[126:129]
	v_mfma_f32_16x16x32_bf16 v[122:125], v[178:181], v[186:189], v[122:125]
	v_mfma_f32_16x16x32_bf16 v[118:121], v[170:173], v[196:199], v[118:121]
	v_mfma_f32_16x16x32_bf16 v[114:117], v[178:181], v[196:199], v[114:117]
	v_mfma_f32_16x16x32_bf16 v[110:113], v[170:173], v[204:207], v[110:113]
	v_mfma_f32_16x16x32_bf16 v[106:109], v[178:181], v[204:207], v[106:109]
	v_mfma_f32_16x16x32_bf16 v[102:105], v[170:173], v[212:215], v[102:105]
	v_mfma_f32_16x16x32_bf16 v[98:101], v[178:181], v[212:215], v[98:101]
	v_mfma_f32_16x16x32_bf16 v[126:129], v[174:177], v[190:193], v[126:129]
	v_mfma_f32_16x16x32_bf16 v[122:125], v[182:185], v[190:193], v[122:125]
	v_mfma_f32_16x16x32_bf16 v[118:121], v[174:177], v[200:203], v[118:121]
	v_mfma_f32_16x16x32_bf16 v[114:117], v[182:185], v[200:203], v[114:117]
	v_mfma_f32_16x16x32_bf16 v[110:113], v[174:177], v[208:211], v[110:113]
	v_mfma_f32_16x16x32_bf16 v[106:109], v[182:185], v[208:211], v[106:109]
	v_mfma_f32_16x16x32_bf16 v[102:105], v[174:177], v[216:219], v[102:105]
	v_mfma_f32_16x16x32_bf16 v[98:101], v[182:185], v[216:219], v[98:101]
	s_setprio 0
	s_barrier
	ds_read_b128 v[220:223], v135
	ds_read_b128 v[224:227], v135 offset:1024
	ds_read_b128 v[228:231], v135 offset:2048
	ds_read_b128 v[232:235], v135 offset:3072
	s_add_u32 s26, s19, 0x180
	s_addc_u32 s27, s20, 0
	v_readfirstlane_b32 s21, v134
	s_mov_b32 m0, s21
	global_load_lds_dwordx4 v132, s[26:27]
	v_readfirstlane_b32 s21, v136
	s_mov_b32 m0, s21
	global_load_lds_dwordx4 v130, s[26:27]
	s_barrier
	s_waitcnt lgkmcnt(0)
	s_setprio 1
	v_mfma_f32_16x16x32_bf16 v[94:97], v[220:223], v[186:189], v[94:97]
	v_mfma_f32_16x16x32_bf16 v[90:93], v[228:231], v[186:189], v[90:93]
	v_mfma_f32_16x16x32_bf16 v[86:89], v[220:223], v[196:199], v[86:89]
	v_mfma_f32_16x16x32_bf16 v[82:85], v[228:231], v[196:199], v[82:85]
	v_mfma_f32_16x16x32_bf16 v[78:81], v[220:223], v[204:207], v[78:81]
	v_mfma_f32_16x16x32_bf16 v[74:77], v[228:231], v[204:207], v[74:77]
	v_mfma_f32_16x16x32_bf16 v[70:73], v[220:223], v[212:215], v[70:73]
	v_mfma_f32_16x16x32_bf16 v[66:69], v[228:231], v[212:215], v[66:69]
	v_mfma_f32_16x16x32_bf16 v[94:97], v[224:227], v[190:193], v[94:97]
	v_mfma_f32_16x16x32_bf16 v[90:93], v[232:235], v[190:193], v[90:93]
	v_mfma_f32_16x16x32_bf16 v[86:89], v[224:227], v[200:203], v[86:89]
	v_mfma_f32_16x16x32_bf16 v[82:85], v[232:235], v[200:203], v[82:85]
	v_mfma_f32_16x16x32_bf16 v[78:81], v[224:227], v[208:211], v[78:81]
	v_mfma_f32_16x16x32_bf16 v[74:77], v[232:235], v[208:211], v[74:77]
	v_mfma_f32_16x16x32_bf16 v[70:73], v[224:227], v[216:219], v[70:73]
	v_mfma_f32_16x16x32_bf16 v[66:69], v[232:235], v[216:219], v[66:69]
	s_setprio 0
	s_barrier
	ds_read_b128 v[186:189], v168 offset:49152
	ds_read_b128 v[190:193], v168 offset:50176
	ds_read_b128 v[196:199], v167 offset:49152
	ds_read_b128 v[200:203], v167 offset:50176
	ds_read_b128 v[204:207], v166 offset:49152
	ds_read_b128 v[208:211], v166 offset:50176
	ds_read_b128 v[212:215], v147 offset:49152
	ds_read_b128 v[216:219], v147 offset:50176
	s_add_u32 s26, s17, 0x8000180
	s_addc_u32 s27, s18, 0
	v_readfirstlane_b32 s17, v140
	s_mov_b32 m0, s17
	global_load_lds_dwordx4 v132, s[26:27]
	v_readfirstlane_b32 s17, v142
	s_mov_b32 m0, s17
	global_load_lds_dwordx4 v130, s[26:27]
	s_barrier
;   #define LDA(dst,b,h) for(int m=0;m<4;++m)for(int k=0;k<2;++k) \
;     dst[m][k]=*reinterpret_cast<const bf16x8*>((char*)SA(b,h)+lds_byte(wr*64+m*16+fr,k*32+fq*8))
;   #define LDB(dst,b,h) for(int n=0;n<2;++n)for(int k=0;k<2;++k) \
;     dst[n][k]=*reinterpret_cast<const bf16x8*>((char*)SB(b,h)+lds_byte(wc*32+n*16+fr,k*32+fq*8))
;   #define MMA(ai,bj,At,Bt_) do{__builtin_amdgcn_s_setprio(1); \
;     for(int m=0;m<4;++m)for(int n=0;n<2;++n)for(int k=0;k<2;++k) \
;       acc[ai][bj][m][n]=__builtin_amdgcn_mfma_f32_16x16x32_bf16(Bt_[n][k],At[m][k],acc[ai][bj][m][n],0,0,0); \
;     __builtin_amdgcn_s_setprio(0);}while(0)
;   #define WAIT_V(n) asm volatile("s_waitcnt vmcnt(" #n ")":::"memory")
;   #define WAIT_L(n) asm volatile("s_waitcnt lgkmcnt(" #n ")":::"memory")
;   #define BAR __builtin_amdgcn_s_barrier()
;   #define SCHED __builtin_amdgcn_sched_barrier(0)
; template <bool TWO, class MID> ...
;     ...
;     BAR; WAIT_L(0); MMA(1,0,At,B0); BAR; SCHED;
;     STAGE_B(SB(1,1),1,t+3);
;     WAIT_V(6); BAR; MMA(1,1,At,B1); BAR;
;   }
;   { LDB(B0,0,0); LDA(At,0,0); STAGE_A(SA(1,1),1,nt-1);
;     BAR; WAIT_L(0); MMA(0,0,At,B0); BAR;
;     LDB(B1,0,1); BAR; WAIT_L(0); MMA(0,1,At,B1); BAR;
	s_waitcnt lgkmcnt(0)
	s_setprio 1
	v_mfma_f32_16x16x32_bf16 v[62:65], v[170:173], v[186:189], v[62:65]
	v_mfma_f32_16x16x32_bf16 v[58:61], v[178:181], v[186:189], v[58:61]
	v_mfma_f32_16x16x32_bf16 v[54:57], v[170:173], v[196:199], v[54:57]
	v_mfma_f32_16x16x32_bf16 v[50:53], v[178:181], v[196:199], v[50:53]
	v_mfma_f32_16x16x32_bf16 v[46:49], v[170:173], v[204:207], v[46:49]
	v_mfma_f32_16x16x32_bf16 v[42:45], v[178:181], v[204:207], v[42:45]
	v_mfma_f32_16x16x32_bf16 v[38:41], v[170:173], v[212:215], v[38:41]
	v_mfma_f32_16x16x32_bf16 v[34:37], v[178:181], v[212:215], v[34:37]
	v_mfma_f32_16x16x32_bf16 v[62:65], v[174:177], v[190:193], v[62:65]
	v_mfma_f32_16x16x32_bf16 v[58:61], v[182:185], v[190:193], v[58:61]
	v_mfma_f32_16x16x32_bf16 v[54:57], v[174:177], v[200:203], v[54:57]
	v_mfma_f32_16x16x32_bf16 v[50:53], v[182:185], v[200:203], v[50:53]
	v_mfma_f32_16x16x32_bf16 v[46:49], v[174:177], v[208:211], v[46:49]
	v_mfma_f32_16x16x32_bf16 v[42:45], v[182:185], v[208:211], v[42:45]
	v_mfma_f32_16x16x32_bf16 v[38:41], v[174:177], v[216:219], v[38:41]
	v_mfma_f32_16x16x32_bf16 v[34:37], v[182:185], v[216:219], v[34:37]
	s_setprio 0
	s_barrier
	s_add_u32 s18, s19, 0x80180
	s_addc_u32 s19, s20, 0
	v_readfirstlane_b32 s17, v144
	s_mov_b32 m0, s17
	global_load_lds_dwordx4 v132, s[18:19]
	v_readfirstlane_b32 s17, v146
	s_mov_b32 m0, s17
	global_load_lds_dwordx4 v130, s[18:19]
	s_waitcnt vmcnt(6)
	s_barrier
	s_setprio 1
	v_mfma_f32_16x16x32_bf16 v[30:33], v[220:223], v[186:189], v[30:33]
	v_mfma_f32_16x16x32_bf16 v[26:29], v[228:231], v[186:189], v[26:29]
	v_mfma_f32_16x16x32_bf16 v[22:25], v[220:223], v[196:199], v[22:25]
	v_mfma_f32_16x16x32_bf16 v[18:21], v[228:231], v[196:199], v[18:21]
	v_mfma_f32_16x16x32_bf16 v[14:17], v[220:223], v[204:207], v[14:17]
	v_mfma_f32_16x16x32_bf16 v[10:13], v[228:231], v[204:207], v[10:13]
	v_mfma_f32_16x16x32_bf16 v[6:9], v[220:223], v[212:215], v[6:9]
	v_mfma_f32_16x16x32_bf16 v[2:5], v[228:231], v[212:215], v[2:5]
	v_mfma_f32_16x16x32_bf16 v[30:33], v[224:227], v[190:193], v[30:33]
	v_mfma_f32_16x16x32_bf16 v[26:29], v[232:235], v[190:193], v[26:29]
	v_mfma_f32_16x16x32_bf16 v[22:25], v[224:227], v[200:203], v[22:25]
	v_mfma_f32_16x16x32_bf16 v[18:21], v[232:235], v[200:203], v[18:21]
	v_mfma_f32_16x16x32_bf16 v[14:17], v[224:227], v[208:211], v[14:17]
	v_mfma_f32_16x16x32_bf16 v[10:13], v[232:235], v[208:211], v[10:13]
	v_mfma_f32_16x16x32_bf16 v[6:9], v[224:227], v[216:219], v[6:9]
	v_mfma_f32_16x16x32_bf16 v[2:5], v[232:235], v[216:219], v[2:5]
	s_setprio 0
	s_add_i32 s9, s9, 2
	s_add_u32 s0, s0, 0x100
	s_addc_u32 s1, s1, 0
	s_cmp_lt_u32 s9, 28
	s_barrier
	s_cbranch_scc1 .LBB0_169
	ds_read_b128 v[150:153], v143
	ds_read_b128 v[158:161], v143 offset:1024
	ds_read_b128 v[162:165], v143 offset:2048
	ds_read_b128 v[142:145], v143 offset:3072
	ds_read_b128 v[170:173], v168
	ds_read_b128 v[174:177], v168 offset:1024
	ds_read_b128 v[178:181], v167
	ds_read_b128 v[182:185], v167 offset:1024
	ds_read_b128 v[186:189], v166
	ds_read_b128 v[190:193], v166 offset:1024
	ds_read_b128 v[196:199], v147
	ds_read_b128 v[200:203], v147 offset:1024
	s_add_u32 s0, s11, 0x80f80
	s_addc_u32 s1, s16, 0
	v_lshl_add_u64 v[132:133], s[0:1], 0, v[132:133]
	v_readfirstlane_b32 s9, v148
	s_mov_b32 m0, s9
	global_load_lds_dwordx4 v[132:133], off
	v_lshl_add_u64 v[130:131], s[0:1], 0, v[130:131]
	v_readfirstlane_b32 s0, v156
	s_mov_b32 m0, s0
	global_load_lds_dwordx4 v[130:131], off
	s_barrier
	s_waitcnt lgkmcnt(0)
	s_setprio 1
	v_mfma_f32_16x16x32_bf16 v[126:129], v[150:153], v[170:173], v[126:129]
	v_mfma_f32_16x16x32_bf16 v[122:125], v[162:165], v[170:173], v[122:125]
	v_mfma_f32_16x16x32_bf16 v[114:117], v[162:165], v[178:181], v[114:117]
	v_mfma_f32_16x16x32_bf16 v[106:109], v[162:165], v[186:189], v[106:109]
	v_mfma_f32_16x16x32_bf16 v[98:101], v[162:165], v[196:199], v[98:101]
	v_mfma_f32_16x16x32_bf16 v[126:129], v[158:161], v[174:177], v[126:129]
	v_mfma_f32_16x16x32_bf16 v[122:125], v[142:145], v[174:177], v[122:125]
	v_mfma_f32_16x16x32_bf16 v[118:121], v[150:153], v[178:181], v[118:121]
	v_mfma_f32_16x16x32_bf16 v[114:117], v[142:145], v[182:185], v[114:117]
	v_mfma_f32_16x16x32_bf16 v[110:113], v[150:153], v[186:189], v[110:113]
	v_mfma_f32_16x16x32_bf16 v[106:109], v[142:145], v[190:193], v[106:109]
	v_mfma_f32_16x16x32_bf16 v[102:105], v[150:153], v[196:199], v[102:105]
	v_mfma_f32_16x16x32_bf16 v[130:133], v[142:145], v[200:203], v[98:101]
	v_mfma_f32_16x16x32_bf16 v[118:121], v[158:161], v[182:185], v[118:121]
	v_mfma_f32_16x16x32_bf16 v[110:113], v[158:161], v[190:193], v[110:113]
	v_mfma_f32_16x16x32_bf16 v[102:105], v[158:161], v[200:203], v[102:105]
	s_setprio 0
	s_barrier
	ds_read_b128 v[98:101], v141
	ds_read_b128 v[154:157], v141 offset:1024
	ds_read_b128 v[204:207], v141 offset:2048
	ds_read_b128 v[138:141], v141 offset:3072
	s_barrier
	s_waitcnt lgkmcnt(0)
	s_setprio 1
	v_mfma_f32_16x16x32_bf16 v[86:89], v[98:101], v[178:181], v[86:89]
	v_mfma_f32_16x16x32_bf16 v[82:85], v[204:207], v[178:181], v[82:85]
	v_mfma_f32_16x16x32_bf16 v[70:73], v[98:101], v[196:199], v[70:73]
	v_mfma_f32_16x16x32_bf16 v[66:69], v[204:207], v[196:199], v[66:69]
	v_mfma_f32_16x16x32_bf16 v[94:97], v[98:101], v[170:173], v[94:97]
	v_mfma_f32_16x16x32_bf16 v[90:93], v[204:207], v[170:173], v[90:93]
	v_mfma_f32_16x16x32_bf16 v[86:89], v[154:157], v[182:185], v[86:89]
	v_mfma_f32_16x16x32_bf16 v[82:85], v[138:141], v[182:185], v[82:85]
	v_mfma_f32_16x16x32_bf16 v[78:81], v[98:101], v[186:189], v[78:81]
	v_mfma_f32_16x16x32_bf16 v[74:77], v[204:207], v[186:189], v[74:77]
	v_mfma_f32_16x16x32_bf16 v[70:73], v[154:157], v[200:203], v[70:73]
	v_mfma_f32_16x16x32_bf16 v[66:69], v[138:141], v[200:203], v[66:69]
	v_mfma_f32_16x16x32_bf16 v[94:97], v[154:157], v[174:177], v[94:97]
	v_mfma_f32_16x16x32_bf16 v[170:173], v[138:141], v[174:177], v[90:93]
	v_mfma_f32_16x16x32_bf16 v[174:177], v[154:157], v[190:193], v[78:81]
	v_mfma_f32_16x16x32_bf16 v[178:181], v[138:141], v[190:193], v[74:77]
	s_setprio 0
	s_barrier
;   #define LDA(dst,b,h) for(int m=0;m<4;++m)for(int k=0;k<2;++k) \
;     dst[m][k]=*reinterpret_cast<const bf16x8*>((char*)SA(b,h)+lds_byte(wr*64+m*16+fr,k*32+fq*8))
;   #define LDB(dst,b,h) for(int n=0;n<2;++n)for(int k=0;k<2;++k) \
;     dst[n][k]=*reinterpret_cast<const bf16x8*>((char*)SB(b,h)+lds_byte(wc*32+n*16+fr,k*32+fq*8))
;   #define MMA(ai,bj,At,Bt_) do{__builtin_amdgcn_s_setprio(1); \
;     for(int m=0;m<4;++m)for(int n=0;n<2;++n)for(int k=0;k<2;++k) \
;       acc[ai][bj][m][n]=__builtin_amdgcn_mfma_f32_16x16x32_bf16(Bt_[n][k],At[m][k],acc[ai][bj][m][n],0,0,0); \
;     __builtin_amdgcn_s_setprio(0);}while(0)
;   #define WAIT_V(n) asm volatile("s_waitcnt vmcnt(" #n ")":::"memory")
;   #define WAIT_L(n) asm volatile("s_waitcnt lgkmcnt(" #n ")":::"memory")
;   #define BAR __builtin_amdgcn_s_barrier()
; template <bool TWO, class MID> ...
;     ...
;     LDA(At,0,1); WAIT_V(4); BAR; WAIT_L(0); MMA(1,0,At,B0); MMA(1,1,At,B1); BAR; }
;   { LDB(B0,1,0); LDA(At,1,0); WAIT_V(2); BAR; WAIT_L(0); MMA(0,0,At,B0); BAR;
	s_nop 0
	ds_read_b128 v[74:77], v168 offset:16384
	ds_read_b128 v[78:81], v168 offset:17408
	ds_read_b128 v[90:93], v167 offset:16384
	ds_read_b128 v[182:185], v167 offset:17408
	ds_read_b128 v[186:189], v166 offset:16384
	ds_read_b128 v[190:193], v166 offset:17408
	ds_read_b128 v[196:199], v147 offset:16384
	ds_read_b128 v[200:203], v147 offset:17408
	s_waitcnt vmcnt(4)
	s_barrier
	s_waitcnt lgkmcnt(0)
	s_setprio 1
	v_mfma_f32_16x16x32_bf16 v[62:65], v[150:153], v[74:77], v[62:65]
	v_mfma_f32_16x16x32_bf16 v[58:61], v[162:165], v[74:77], v[58:61]
	v_mfma_f32_16x16x32_bf16 v[54:57], v[150:153], v[90:93], v[54:57]
	v_mfma_f32_16x16x32_bf16 v[50:53], v[162:165], v[90:93], v[50:53]
	v_mfma_f32_16x16x32_bf16 v[38:41], v[150:153], v[196:199], v[38:41]
	v_mfma_f32_16x16x32_bf16 v[34:37], v[162:165], v[196:199], v[34:37]
	v_mfma_f32_16x16x32_bf16 v[62:65], v[158:161], v[78:81], v[62:65]
	v_mfma_f32_16x16x32_bf16 v[58:61], v[142:145], v[78:81], v[58:61]
	v_mfma_f32_16x16x32_bf16 v[54:57], v[158:161], v[182:185], v[54:57]
	v_mfma_f32_16x16x32_bf16 v[50:53], v[142:145], v[182:185], v[50:53]
	v_mfma_f32_16x16x32_bf16 v[46:49], v[150:153], v[186:189], v[46:49]
	v_mfma_f32_16x16x32_bf16 v[42:45], v[162:165], v[186:189], v[42:45]
	v_mfma_f32_16x16x32_bf16 v[38:41], v[158:161], v[200:203], v[38:41]
	v_mfma_f32_16x16x32_bf16 v[34:37], v[142:145], v[200:203], v[34:37]
	v_mfma_f32_16x16x32_bf16 v[208:211], v[158:161], v[190:193], v[46:49]
	v_mfma_f32_16x16x32_bf16 v[212:215], v[142:145], v[190:193], v[42:45]
	s_setprio 0
	s_setprio 1
	v_mfma_f32_16x16x32_bf16 v[22:25], v[98:101], v[90:93], v[22:25]
	v_mfma_f32_16x16x32_bf16 v[18:21], v[204:207], v[90:93], v[18:21]
	v_mfma_f32_16x16x32_bf16 v[6:9], v[98:101], v[196:199], v[6:9]
	v_mfma_f32_16x16x32_bf16 v[2:5], v[204:207], v[196:199], v[2:5]
	v_mfma_f32_16x16x32_bf16 v[30:33], v[98:101], v[74:77], v[30:33]
	v_mfma_f32_16x16x32_bf16 v[26:29], v[204:207], v[74:77], v[26:29]
	v_mfma_f32_16x16x32_bf16 v[22:25], v[154:157], v[182:185], v[22:25]
	v_mfma_f32_16x16x32_bf16 v[18:21], v[138:141], v[182:185], v[18:21]
	v_mfma_f32_16x16x32_bf16 v[14:17], v[98:101], v[186:189], v[14:17]
	v_mfma_f32_16x16x32_bf16 v[10:13], v[204:207], v[186:189], v[10:13]
	v_mfma_f32_16x16x32_bf16 v[6:9], v[154:157], v[200:203], v[6:9]
	v_mfma_f32_16x16x32_bf16 v[2:5], v[138:141], v[200:203], v[2:5]
	v_mfma_f32_16x16x32_bf16 v[148:151], v[154:157], v[78:81], v[30:33]
	v_mfma_f32_16x16x32_bf16 v[158:161], v[138:141], v[78:81], v[26:29]
	v_mfma_f32_16x16x32_bf16 v[162:165], v[154:157], v[190:193], v[14:17]
	v_mfma_f32_16x16x32_bf16 v[182:185], v[138:141], v[190:193], v[10:13]
	s_setprio 0
	s_barrier
	s_nop 0
	ds_read_b128 v[10:13], v137
	ds_read_b128 v[14:17], v137 offset:1024
	ds_read_b128 v[152:155], v137 offset:2048
	ds_read_b128 v[186:189], v137 offset:3072
	ds_read_b128 v[26:29], v168 offset:32768
	ds_read_b128 v[30:33], v168 offset:33792
	ds_read_b128 v[42:45], v167 offset:32768
	ds_read_b128 v[46:49], v167 offset:33792
	ds_read_b128 v[190:193], v166 offset:32768
	ds_read_b128 v[196:199], v166 offset:33792
	ds_read_b128 v[200:203], v147 offset:32768
	ds_read_b128 v[204:207], v147 offset:33792
	s_waitcnt vmcnt(2)
	s_barrier
	s_waitcnt lgkmcnt(0)
	s_setprio 1
	v_mfma_f32_16x16x32_bf16 v[74:77], v[10:13], v[26:29], v[126:129]
	v_mfma_f32_16x16x32_bf16 v[142:145], v[14:17], v[30:33], v[74:77]
	v_mfma_f32_16x16x32_bf16 v[74:77], v[152:155], v[26:29], v[122:125]
	v_mfma_f32_16x16x32_bf16 v[138:141], v[186:189], v[30:33], v[74:77]
	v_mfma_f32_16x16x32_bf16 v[74:77], v[10:13], v[42:45], v[118:121]
	v_mfma_f32_16x16x32_bf16 v[126:129], v[14:17], v[46:49], v[74:77]
	v_mfma_f32_16x16x32_bf16 v[74:77], v[152:155], v[42:45], v[114:117]
	v_mfma_f32_16x16x32_bf16 v[122:125], v[186:189], v[46:49], v[74:77]
	v_mfma_f32_16x16x32_bf16 v[74:77], v[10:13], v[190:193], v[110:113]
	v_mfma_f32_16x16x32_bf16 v[98:101], v[14:17], v[196:199], v[74:77]
	v_mfma_f32_16x16x32_bf16 v[74:77], v[152:155], v[190:193], v[106:109]
	v_mfma_f32_16x16x32_bf16 v[90:93], v[186:189], v[196:199], v[74:77]
	v_mfma_f32_16x16x32_bf16 v[74:77], v[10:13], v[200:203], v[102:105]
	v_mfma_f32_16x16x32_bf16 v[78:81], v[14:17], v[204:207], v[74:77]
	v_mfma_f32_16x16x32_bf16 v[74:77], v[152:155], v[200:203], v[130:133]
	v_mfma_f32_16x16x32_bf16 v[74:77], v[186:189], v[204:207], v[74:77]
	s_setprio 0
	s_barrier
;   #define LDA(dst,b,h) for(int m=0;m<4;++m)for(int k=0;k<2;++k) \
;     dst[m][k]=*reinterpret_cast<const bf16x8*>((char*)SA(b,h)+lds_byte(wr*64+m*16+fr,k*32+fq*8))
;   #define LDB(dst,b,h) for(int n=0;n<2;++n)for(int k=0;k<2;++k) \
;     dst[n][k]=*reinterpret_cast<const bf16x8*>((char*)SB(b,h)+lds_byte(wc*32+n*16+fr,k*32+fq*8))
;   #define MMA(ai,bj,At,Bt_) do{__builtin_amdgcn_s_setprio(1); \
;     for(int m=0;m<4;++m)for(int n=0;n<2;++n)for(int k=0;k<2;++k) \
;       acc[ai][bj][m][n]=__builtin_amdgcn_mfma_f32_16x16x32_bf16(Bt_[n][k],At[m][k],acc[ai][bj][m][n],0,0,0); \
;     __builtin_amdgcn_s_setprio(0);}while(0)
;   #define WAIT_V(n) asm volatile("s_waitcnt vmcnt(" #n ")":::"memory")
;   #define WAIT_L(n) asm volatile("s_waitcnt lgkmcnt(" #n ")":::"memory")
;   #define BAR __builtin_amdgcn_s_barrier()
; template <bool TWO, class MID> ...
;     ...
;     LDB(B1,1,1); WAIT_V(0); BAR; WAIT_L(0); MMA(0,1,At,B1); BAR;
;     LDA(At,1,1); BAR; WAIT_L(0); MMA(1,0,At,B0); MMA(1,1,At,B1); BAR; }
;   if(wr==0)BAR;
	ds_read_b128 v[102:105], v135
	ds_read_b128 v[110:113], v135 offset:1024
	ds_read_b128 v[118:121], v135 offset:2048
	ds_read_b128 v[216:219], v135 offset:3072
	s_waitcnt vmcnt(0)
	s_barrier
	s_waitcnt lgkmcnt(0)
	s_setprio 1
	v_mfma_f32_16x16x32_bf16 v[94:97], v[102:105], v[26:29], v[94:97]
	v_mfma_f32_16x16x32_bf16 v[26:29], v[118:121], v[26:29], v[170:173]
	v_mfma_f32_16x16x32_bf16 v[130:133], v[216:219], v[30:33], v[26:29]
	v_mfma_f32_16x16x32_bf16 v[26:29], v[102:105], v[42:45], v[86:89]
	v_mfma_f32_16x16x32_bf16 v[114:117], v[110:113], v[46:49], v[26:29]
	v_mfma_f32_16x16x32_bf16 v[26:29], v[118:121], v[42:45], v[82:85]
	v_mfma_f32_16x16x32_bf16 v[106:109], v[216:219], v[46:49], v[26:29]
	v_mfma_f32_16x16x32_bf16 v[26:29], v[102:105], v[190:193], v[174:177]
	v_mfma_f32_16x16x32_bf16 v[86:89], v[110:113], v[196:199], v[26:29]
	v_mfma_f32_16x16x32_bf16 v[26:29], v[118:121], v[190:193], v[178:181]
	v_mfma_f32_16x16x32_bf16 v[82:85], v[216:219], v[196:199], v[26:29]
	v_mfma_f32_16x16x32_bf16 v[26:29], v[102:105], v[200:203], v[70:73]
	v_mfma_f32_16x16x32_bf16 v[70:73], v[110:113], v[204:207], v[26:29]
	v_mfma_f32_16x16x32_bf16 v[26:29], v[118:121], v[200:203], v[66:69]
	v_mfma_f32_16x16x32_bf16 v[134:137], v[110:113], v[30:33], v[94:97]
	v_mfma_f32_16x16x32_bf16 v[66:69], v[216:219], v[204:207], v[26:29]
	s_setprio 0
	s_barrier
	ds_read_b128 v[94:97], v168 offset:49152
	ds_read_b128 v[168:171], v168 offset:50176
	ds_read_b128 v[172:175], v167 offset:49152
	ds_read_b128 v[176:179], v167 offset:50176
	ds_read_b128 v[190:193], v166 offset:49152
	ds_read_b128 v[196:199], v166 offset:50176
	ds_read_b128 v[200:203], v147 offset:49152
	ds_read_b128 v[204:207], v147 offset:50176
	s_barrier
	s_waitcnt lgkmcnt(0)
	s_setprio 1
	v_mfma_f32_16x16x32_bf16 v[26:29], v[10:13], v[94:97], v[62:65]
	v_mfma_f32_16x16x32_bf16 v[62:65], v[14:17], v[168:171], v[26:29]
	v_mfma_f32_16x16x32_bf16 v[26:29], v[152:155], v[94:97], v[58:61]
	v_mfma_f32_16x16x32_bf16 v[58:61], v[186:189], v[168:171], v[26:29]
	v_mfma_f32_16x16x32_bf16 v[26:29], v[10:13], v[172:175], v[54:57]
	v_mfma_f32_16x16x32_bf16 v[46:49], v[14:17], v[176:179], v[26:29]
	v_mfma_f32_16x16x32_bf16 v[26:29], v[152:155], v[172:175], v[50:53]
	v_mfma_f32_16x16x32_bf16 v[42:45], v[186:189], v[176:179], v[26:29]
	v_mfma_f32_16x16x32_bf16 v[26:29], v[10:13], v[190:193], v[208:211]
	v_mfma_f32_16x16x32_bf16 v[10:13], v[10:13], v[200:203], v[38:41]
	v_mfma_f32_16x16x32_bf16 v[30:33], v[14:17], v[196:199], v[26:29]
	v_mfma_f32_16x16x32_bf16 v[26:29], v[152:155], v[190:193], v[212:215]
	v_mfma_f32_16x16x32_bf16 v[14:17], v[14:17], v[204:207], v[10:13]
	v_mfma_f32_16x16x32_bf16 v[10:13], v[152:155], v[200:203], v[34:37]
	v_mfma_f32_16x16x32_bf16 v[26:29], v[186:189], v[196:199], v[26:29]
	v_mfma_f32_16x16x32_bf16 v[10:13], v[186:189], v[204:207], v[10:13]
	s_setprio 0
	s_setprio 1
	v_mfma_f32_16x16x32_bf16 v[34:37], v[102:105], v[94:97], v[148:151]
	v_mfma_f32_16x16x32_bf16 v[54:57], v[110:113], v[168:171], v[34:37]
	v_mfma_f32_16x16x32_bf16 v[34:37], v[118:121], v[94:97], v[158:161]
	v_mfma_f32_16x16x32_bf16 v[18:21], v[118:121], v[172:175], v[18:21]
	v_mfma_f32_16x16x32_bf16 v[50:53], v[216:219], v[168:171], v[34:37]
	v_mfma_f32_16x16x32_bf16 v[22:25], v[102:105], v[172:175], v[22:25]
	v_mfma_f32_16x16x32_bf16 v[34:37], v[216:219], v[176:179], v[18:21]
	v_mfma_f32_16x16x32_bf16 v[18:21], v[102:105], v[190:193], v[162:165]
	v_mfma_f32_16x16x32_bf16 v[38:41], v[110:113], v[176:179], v[22:25]
	v_mfma_f32_16x16x32_bf16 v[22:25], v[110:113], v[196:199], v[18:21]
	v_mfma_f32_16x16x32_bf16 v[18:21], v[118:121], v[190:193], v[182:185]
	v_mfma_f32_16x16x32_bf16 v[6:9], v[102:105], v[200:203], v[6:9]
	v_mfma_f32_16x16x32_bf16 v[2:5], v[118:121], v[200:203], v[2:5]
	v_mfma_f32_16x16x32_bf16 v[18:21], v[216:219], v[196:199], v[18:21]
	v_mfma_f32_16x16x32_bf16 v[6:9], v[110:113], v[204:207], v[6:9]
	v_mfma_f32_16x16x32_bf16 v[2:5], v[216:219], v[204:207], v[2:5]
	s_setprio 0
	v_cmp_gt_u32_e32 vcc, s30, v1
	s_barrier
	s_and_saveexec_b64 s[0:1], vcc
	s_cbranch_execz .LBB0_172
	s_barrier

;   #define LDA(dst,b,h) for(int m=0;m<4;++m)for(int k=0;k<2;++k) \
;     dst[m][k]=*reinterpret_cast<const bf16x8*>((char*)SA(b,h)+lds_byte(wr*64+m*16+fr,k*32+fq*8))
;   #define LDB(dst,b,h) for(int n=0;n<2;++n)for(int k=0;k<2;++k) \
;     dst[n][k]=*reinterpret_cast<const bf16x8*>((char*)SB(b,h)+lds_byte(wc*32+n*16+fr,k*32+fq*8))
;   #define MMA(ai,bj,At,Bt_) do{__builtin_amdgcn_s_setprio(1); \
;     for(int m=0;m<4;++m)for(int n=0;n<2;++n)for(int k=0;k<2;++k) \
;       acc[ai][bj][m][n]=__builtin_amdgcn_mfma_f32_16x16x32_bf16(Bt_[n][k],At[m][k],acc[ai][bj][m][n],0,0,0); \
;     __builtin_amdgcn_s_setprio(0);}while(0)
;   #define WAIT_V(n) asm volatile("s_waitcnt vmcnt(" #n ")":::"memory")
;   #define WAIT_L(n) asm volatile("s_waitcnt lgkmcnt(" #n ")":::"memory")
;   #define BAR __builtin_amdgcn_s_barrier()
;   #define SCHED __builtin_amdgcn_sched_barrier(0)
; __device__ __forceinline__ void gll16(const void* g, const void* l) {
;   const unsigned m = __builtin_amdgcn_readfirstlane((unsigned)(uintptr_t)l);
;   asm volatile("s_mov_b32 m0, %0\n\tglobal_load_lds_dwordx4 %1, off" :: "s"(m), "v"(g) : "memory");
; }
; template <bool TWO, class MID> ...
;     ...
;     LDB(B0,0,0); SCHED; LDA(At,0,0); STAGE_A(SA(1,1),1,t+1);
;     WAIT_L(8); BAR; WAIT_L(0); MMA(0,0,At,B0); BAR; SCHED;
;     LDB(B1,0,1); STAGE_B(SB(0,0),0,t+2);
;     BAR; WAIT_L(0); MMA(0,1,At,B1); BAR;
;     LDA(At,0,1); STAGE_A(SA(0,0),0,t+2);
;     BAR; WAIT_L(0); MMA(1,0,At,B0); BAR; SCHED;
;     STAGE_B(SB(0,1),1,t+2);
;     WAIT_V(6); BAR; MMA(1,1,At,B1); BAR;
.LBB0_489:
	ds_read_b128 v[166:169], v149
	ds_read_b128 v[170:173], v149 offset:1024
	ds_read_b128 v[174:177], v149 offset:2048
	ds_read_b128 v[178:181], v149 offset:3072
	ds_read_b128 v[182:185], v141
	ds_read_b128 v[186:189], v141 offset:1024
	ds_read_b128 v[190:193], v139
	ds_read_b128 v[196:199], v139 offset:1024
	ds_read_b128 v[200:203], v137
	ds_read_b128 v[204:207], v137 offset:1024
	ds_read_b128 v[208:211], v135
	ds_read_b128 v[212:215], v135 offset:1024
	s_add_u32 s19, s4, s10
	s_addc_u32 s24, s5, s11
	s_add_u32 s26, s19, 0x36080080
	s_addc_u32 s27, s24, 0
	v_readfirstlane_b32 s25, v148
	s_mov_b32 m0, s25
	global_load_lds_dwordx4 v132, s[26:27]
	v_readfirstlane_b32 s25, v150
	s_mov_b32 m0, s25
	global_load_lds_dwordx4 v130, s[26:27]
	s_waitcnt lgkmcnt(8)
	s_barrier
	s_waitcnt lgkmcnt(0)
	s_setprio 1
	v_mfma_f32_16x16x32_bf16 v[126:129], v[166:169], v[182:185], v[126:129]
	v_mfma_f32_16x16x32_bf16 v[122:125], v[174:177], v[182:185], v[122:125]
	v_mfma_f32_16x16x32_bf16 v[118:121], v[166:169], v[190:193], v[118:121]
	v_mfma_f32_16x16x32_bf16 v[114:117], v[174:177], v[190:193], v[114:117]
	v_mfma_f32_16x16x32_bf16 v[110:113], v[166:169], v[200:203], v[110:113]
	v_mfma_f32_16x16x32_bf16 v[106:109], v[174:177], v[200:203], v[106:109]
	v_mfma_f32_16x16x32_bf16 v[102:105], v[166:169], v[208:211], v[102:105]
	v_mfma_f32_16x16x32_bf16 v[98:101], v[174:177], v[208:211], v[98:101]
	v_mfma_f32_16x16x32_bf16 v[126:129], v[170:173], v[186:189], v[126:129]
	v_mfma_f32_16x16x32_bf16 v[122:125], v[178:181], v[186:189], v[122:125]
	v_mfma_f32_16x16x32_bf16 v[118:121], v[170:173], v[196:199], v[118:121]
	v_mfma_f32_16x16x32_bf16 v[114:117], v[178:181], v[196:199], v[114:117]
	v_mfma_f32_16x16x32_bf16 v[110:113], v[170:173], v[204:207], v[110:113]
	v_mfma_f32_16x16x32_bf16 v[106:109], v[178:181], v[204:207], v[106:109]
	v_mfma_f32_16x16x32_bf16 v[102:105], v[170:173], v[212:215], v[102:105]
	v_mfma_f32_16x16x32_bf16 v[98:101], v[178:181], v[212:215], v[98:101]
	s_setprio 0
	s_barrier
	s_add_u32 s25, s4, s16
	ds_read_b128 v[216:219], v147
	ds_read_b128 v[220:223], v147 offset:1024
	ds_read_b128 v[224:227], v147 offset:2048
	ds_read_b128 v[228:231], v147 offset:3072
	s_addc_u32 s26, s5, s17
	s_add_u32 s28, s25, 0x3400100
	s_addc_u32 s29, s26, 0
	v_readfirstlane_b32 s27, v152
	s_mov_b32 m0, s27
	global_load_lds_dwordx4 v132, s[28:29]
	v_readfirstlane_b32 s27, v154
	s_mov_b32 m0, s27
	global_load_lds_dwordx4 v130, s[28:29]
	s_barrier
	s_waitcnt lgkmcnt(0)
	s_setprio 1
	v_mfma_f32_16x16x32_bf16 v[94:97], v[216:219], v[182:185], v[94:97]
	v_mfma_f32_16x16x32_bf16 v[90:93], v[224:227], v[182:185], v[90:93]
	v_mfma_f32_16x16x32_bf16 v[86:89], v[216:219], v[190:193], v[86:89]
	v_mfma_f32_16x16x32_bf16 v[82:85], v[224:227], v[190:193], v[82:85]
	v_mfma_f32_16x16x32_bf16 v[78:81], v[216:219], v[200:203], v[78:81]
	v_mfma_f32_16x16x32_bf16 v[74:77], v[224:227], v[200:203], v[74:77]
	v_mfma_f32_16x16x32_bf16 v[70:73], v[216:219], v[208:211], v[70:73]
	v_mfma_f32_16x16x32_bf16 v[66:69], v[224:227], v[208:211], v[66:69]
	v_mfma_f32_16x16x32_bf16 v[94:97], v[220:223], v[186:189], v[94:97]
	v_mfma_f32_16x16x32_bf16 v[90:93], v[228:231], v[186:189], v[90:93]
	v_mfma_f32_16x16x32_bf16 v[86:89], v[220:223], v[196:199], v[86:89]
	v_mfma_f32_16x16x32_bf16 v[82:85], v[228:231], v[196:199], v[82:85]
	v_mfma_f32_16x16x32_bf16 v[78:81], v[220:223], v[204:207], v[78:81]
	v_mfma_f32_16x16x32_bf16 v[74:77], v[228:231], v[204:207], v[74:77]
	v_mfma_f32_16x16x32_bf16 v[70:73], v[220:223], v[212:215], v[70:73]
	v_mfma_f32_16x16x32_bf16 v[66:69], v[228:231], v[212:215], v[66:69]
	s_setprio 0
	s_barrier
	ds_read_b128 v[182:185], v141 offset:16384
	ds_read_b128 v[186:189], v141 offset:17408
	ds_read_b128 v[190:193], v139 offset:16384
	ds_read_b128 v[196:199], v139 offset:17408
	ds_read_b128 v[200:203], v137 offset:16384
	ds_read_b128 v[204:207], v137 offset:17408
	ds_read_b128 v[208:211], v135 offset:16384
	ds_read_b128 v[212:215], v135 offset:17408
	s_add_u32 s28, s19, 0x36000100
	s_addc_u32 s29, s24, 0
	v_readfirstlane_b32 s27, v138
	s_mov_b32 m0, s27
	global_load_lds_dwordx4 v132, s[28:29]
	v_readfirstlane_b32 s27, v156
	s_mov_b32 m0, s27
	global_load_lds_dwordx4 v130, s[28:29]
	s_barrier
	s_waitcnt lgkmcnt(0)
	s_setprio 1
	v_mfma_f32_16x16x32_bf16 v[62:65], v[166:169], v[182:185], v[62:65]
	v_mfma_f32_16x16x32_bf16 v[58:61], v[174:177], v[182:185], v[58:61]
	v_mfma_f32_16x16x32_bf16 v[54:57], v[166:169], v[190:193], v[54:57]
	v_mfma_f32_16x16x32_bf16 v[50:53], v[174:177], v[190:193], v[50:53]
	v_mfma_f32_16x16x32_bf16 v[46:49], v[166:169], v[200:203], v[46:49]
	v_mfma_f32_16x16x32_bf16 v[42:45], v[174:177], v[200:203], v[42:45]
	v_mfma_f32_16x16x32_bf16 v[38:41], v[166:169], v[208:211], v[38:41]
	v_mfma_f32_16x16x32_bf16 v[34:37], v[174:177], v[208:211], v[34:37]
	v_mfma_f32_16x16x32_bf16 v[62:65], v[170:173], v[186:189], v[62:65]
	v_mfma_f32_16x16x32_bf16 v[58:61], v[178:181], v[186:189], v[58:61]
	v_mfma_f32_16x16x32_bf16 v[54:57], v[170:173], v[196:199], v[54:57]
	v_mfma_f32_16x16x32_bf16 v[50:53], v[178:181], v[196:199], v[50:53]
	v_mfma_f32_16x16x32_bf16 v[46:49], v[170:173], v[204:207], v[46:49]
	v_mfma_f32_16x16x32_bf16 v[42:45], v[178:181], v[204:207], v[42:45]
	v_mfma_f32_16x16x32_bf16 v[38:41], v[170:173], v[212:215], v[38:41]
	v_mfma_f32_16x16x32_bf16 v[34:37], v[178:181], v[212:215], v[34:37]
	s_setprio 0
	s_barrier
	s_add_u32 s28, s25, 0x3480100
	s_addc_u32 s29, s26, 0
	v_readfirstlane_b32 s27, v158
	s_mov_b32 m0, s27
	global_load_lds_dwordx4 v132, s[28:29]
	v_readfirstlane_b32 s27, v160
	s_mov_b32 m0, s27
	global_load_lds_dwordx4 v130, s[28:29]
	s_waitcnt vmcnt(6)
	s_barrier
;   #define LDA(dst,b,h) for(int m=0;m<4;++m)for(int k=0;k<2;++k) \
;     dst[m][k]=*reinterpret_cast<const bf16x8*>((char*)SA(b,h)+lds_byte(wr*64+m*16+fr,k*32+fq*8))
;   #define LDB(dst,b,h) for(int n=0;n<2;++n)for(int k=0;k<2;++k) \
;     dst[n][k]=*reinterpret_cast<const bf16x8*>((char*)SB(b,h)+lds_byte(wc*32+n*16+fr,k*32+fq*8))
;   #define MMA(ai,bj,At,Bt_) do{__builtin_amdgcn_s_setprio(1); \
;     for(int m=0;m<4;++m)for(int n=0;n<2;++n)for(int k=0;k<2;++k) \
;       acc[ai][bj][m][n]=__builtin_amdgcn_mfma_f32_16x16x32_bf16(Bt_[n][k],At[m][k],acc[ai][bj][m][n],0,0,0); \
;     __builtin_amdgcn_s_setprio(0);}while(0)
;   #define WAIT_V(n) asm volatile("s_waitcnt vmcnt(" #n ")":::"memory")
;   #define WAIT_L(n) asm volatile("s_waitcnt lgkmcnt(" #n ")":::"memory")
;   #define BAR __builtin_amdgcn_s_barrier()
;   #define SCHED __builtin_amdgcn_sched_barrier(0)
; __device__ __forceinline__ void gll16(const void* g, const void* l) {
;   const unsigned m = __builtin_amdgcn_readfirstlane((unsigned)(uintptr_t)l);
;   asm volatile("s_mov_b32 m0, %0\n\tglobal_load_lds_dwordx4 %1, off" :: "s"(m), "v"(g) : "memory");
; }
; template <bool TWO, class MID> ...
;     ...
;     WAIT_V(6); BAR; MMA(1,1,At,B1); BAR;
;     LDB(B0,1,0); SCHED; LDA(At,1,0); STAGE_A(SA(0,1),1,t+2);
;     WAIT_L(8); BAR; WAIT_L(0); MMA(0,0,At,B0); BAR; SCHED;
;     LDB(B1,1,1); STAGE_B(SB(1,0),0,t+3);
;     BAR; WAIT_L(0); MMA(0,1,At,B1); BAR;
;     LDA(At,1,1); STAGE_A(SA(1,0),0,t+3);
	s_setprio 1
	v_mfma_f32_16x16x32_bf16 v[30:33], v[216:219], v[182:185], v[30:33]
	v_mfma_f32_16x16x32_bf16 v[26:29], v[224:227], v[182:185], v[26:29]
	v_mfma_f32_16x16x32_bf16 v[22:25], v[216:219], v[190:193], v[22:25]
	v_mfma_f32_16x16x32_bf16 v[18:21], v[224:227], v[190:193], v[18:21]
	v_mfma_f32_16x16x32_bf16 v[14:17], v[216:219], v[200:203], v[14:17]
	v_mfma_f32_16x16x32_bf16 v[10:13], v[224:227], v[200:203], v[10:13]
	v_mfma_f32_16x16x32_bf16 v[6:9], v[216:219], v[208:211], v[6:9]
	v_mfma_f32_16x16x32_bf16 v[2:5], v[224:227], v[208:211], v[2:5]
	v_mfma_f32_16x16x32_bf16 v[30:33], v[220:223], v[186:189], v[30:33]
	v_mfma_f32_16x16x32_bf16 v[26:29], v[228:231], v[186:189], v[26:29]
	v_mfma_f32_16x16x32_bf16 v[22:25], v[220:223], v[196:199], v[22:25]
	v_mfma_f32_16x16x32_bf16 v[18:21], v[228:231], v[196:199], v[18:21]
	v_mfma_f32_16x16x32_bf16 v[14:17], v[220:223], v[204:207], v[14:17]
	v_mfma_f32_16x16x32_bf16 v[10:13], v[228:231], v[204:207], v[10:13]
	v_mfma_f32_16x16x32_bf16 v[6:9], v[220:223], v[212:215], v[6:9]
	v_mfma_f32_16x16x32_bf16 v[2:5], v[228:231], v[212:215], v[2:5]
	s_setprio 0
	s_barrier
	ds_read_b128 v[166:169], v145
	ds_read_b128 v[170:173], v145 offset:1024
	ds_read_b128 v[174:177], v145 offset:2048
	ds_read_b128 v[178:181], v145 offset:3072
	ds_read_b128 v[182:185], v141 offset:32768
	ds_read_b128 v[186:189], v141 offset:33792
	ds_read_b128 v[190:193], v139 offset:32768
	ds_read_b128 v[196:199], v139 offset:33792
	ds_read_b128 v[200:203], v137 offset:32768
	ds_read_b128 v[204:207], v137 offset:33792
	ds_read_b128 v[208:211], v135 offset:32768
	ds_read_b128 v[212:215], v135 offset:33792
	s_add_u32 s28, s19, 0x36080100
	s_addc_u32 s29, s24, 0
	v_readfirstlane_b32 s27, v162
	s_mov_b32 m0, s27
	global_load_lds_dwordx4 v132, s[28:29]
	v_readfirstlane_b32 s27, v164
	s_mov_b32 m0, s27
	global_load_lds_dwordx4 v130, s[28:29]
	s_waitcnt lgkmcnt(8)
	s_barrier
	s_waitcnt lgkmcnt(0)
	s_setprio 1
	v_mfma_f32_16x16x32_bf16 v[126:129], v[166:169], v[182:185], v[126:129]
	v_mfma_f32_16x16x32_bf16 v[122:125], v[174:177], v[182:185], v[122:125]
	v_mfma_f32_16x16x32_bf16 v[118:121], v[166:169], v[190:193], v[118:121]
	v_mfma_f32_16x16x32_bf16 v[114:117], v[174:177], v[190:193], v[114:117]
	v_mfma_f32_16x16x32_bf16 v[110:113], v[166:169], v[200:203], v[110:113]
	v_mfma_f32_16x16x32_bf16 v[106:109], v[174:177], v[200:203], v[106:109]
	v_mfma_f32_16x16x32_bf16 v[102:105], v[166:169], v[208:211], v[102:105]
	v_mfma_f32_16x16x32_bf16 v[98:101], v[174:177], v[208:211], v[98:101]
	v_mfma_f32_16x16x32_bf16 v[126:129], v[170:173], v[186:189], v[126:129]
	v_mfma_f32_16x16x32_bf16 v[122:125], v[178:181], v[186:189], v[122:125]
	v_mfma_f32_16x16x32_bf16 v[118:121], v[170:173], v[196:199], v[118:121]
	v_mfma_f32_16x16x32_bf16 v[114:117], v[178:181], v[196:199], v[114:117]
	v_mfma_f32_16x16x32_bf16 v[110:113], v[170:173], v[204:207], v[110:113]
	v_mfma_f32_16x16x32_bf16 v[106:109], v[178:181], v[204:207], v[106:109]
	v_mfma_f32_16x16x32_bf16 v[102:105], v[170:173], v[212:215], v[102:105]
	v_mfma_f32_16x16x32_bf16 v[98:101], v[178:181], v[212:215], v[98:101]
	s_setprio 0
	s_barrier
	ds_read_b128 v[216:219], v143
	ds_read_b128 v[220:223], v143 offset:1024
	ds_read_b128 v[224:227], v143 offset:2048
	ds_read_b128 v[228:231], v143 offset:3072
	s_add_u32 s28, s25, 0x3400180
	s_addc_u32 s29, s26, 0
	v_readfirstlane_b32 s27, v134
	s_mov_b32 m0, s27
	global_load_lds_dwordx4 v132, s[28:29]
	v_readfirstlane_b32 s27, v136
	s_mov_b32 m0, s27
	global_load_lds_dwordx4 v130, s[28:29]
	s_barrier
	s_waitcnt lgkmcnt(0)
	s_setprio 1
	v_mfma_f32_16x16x32_bf16 v[94:97], v[216:219], v[182:185], v[94:97]
	v_mfma_f32_16x16x32_bf16 v[90:93], v[224:227], v[182:185], v[90:93]
	v_mfma_f32_16x16x32_bf16 v[86:89], v[216:219], v[190:193], v[86:89]
	v_mfma_f32_16x16x32_bf16 v[82:85], v[224:227], v[190:193], v[82:85]
	v_mfma_f32_16x16x32_bf16 v[78:81], v[216:219], v[200:203], v[78:81]
	v_mfma_f32_16x16x32_bf16 v[74:77], v[224:227], v[200:203], v[74:77]
	v_mfma_f32_16x16x32_bf16 v[70:73], v[216:219], v[208:211], v[70:73]
	v_mfma_f32_16x16x32_bf16 v[66:69], v[224:227], v[208:211], v[66:69]
	v_mfma_f32_16x16x32_bf16 v[94:97], v[220:223], v[186:189], v[94:97]
	v_mfma_f32_16x16x32_bf16 v[90:93], v[228:231], v[186:189], v[90:93]
	v_mfma_f32_16x16x32_bf16 v[86:89], v[220:223], v[196:199], v[86:89]
	v_mfma_f32_16x16x32_bf16 v[82:85], v[228:231], v[196:199], v[82:85]
	v_mfma_f32_16x16x32_bf16 v[78:81], v[220:223], v[204:207], v[78:81]
	v_mfma_f32_16x16x32_bf16 v[74:77], v[228:231], v[204:207], v[74:77]
	v_mfma_f32_16x16x32_bf16 v[70:73], v[220:223], v[212:215], v[70:73]
	v_mfma_f32_16x16x32_bf16 v[66:69], v[228:231], v[212:215], v[66:69]
	s_setprio 0
	s_barrier
	ds_read_b128 v[182:185], v141 offset:49152
	ds_read_b128 v[186:189], v141 offset:50176
	ds_read_b128 v[190:193], v139 offset:49152
	ds_read_b128 v[196:199], v139 offset:50176
	ds_read_b128 v[200:203], v137 offset:49152
	ds_read_b128 v[204:207], v137 offset:50176
	ds_read_b128 v[208:211], v135 offset:49152
	ds_read_b128 v[212:215], v135 offset:50176
	s_add_u32 s28, s19, 0x36000180
	s_addc_u32 s29, s24, 0
	v_readfirstlane_b32 s19, v140
	s_mov_b32 m0, s19
	global_load_lds_dwordx4 v132, s[28:29]
	v_readfirstlane_b32 s19, v142
	s_mov_b32 m0, s19
	global_load_lds_dwordx4 v130, s[28:29]
	s_barrier
;   #define LDA(dst,b,h) for(int m=0;m<4;++m)for(int k=0;k<2;++k) \
;     dst[m][k]=*reinterpret_cast<const bf16x8*>((char*)SA(b,h)+lds_byte(wr*64+m*16+fr,k*32+fq*8))
;   #define LDB(dst,b,h) for(int n=0;n<2;++n)for(int k=0;k<2;++k) \
;     dst[n][k]=*reinterpret_cast<const bf16x8*>((char*)SB(b,h)+lds_byte(wc*32+n*16+fr,k*32+fq*8))
;   #define MMA(ai,bj,At,Bt_) do{__builtin_amdgcn_s_setprio(1); \
;     for(int m=0;m<4;++m)for(int n=0;n<2;++n)for(int k=0;k<2;++k) \
;       acc[ai][bj][m][n]=__builtin_amdgcn_mfma_f32_16x16x32_bf16(Bt_[n][k],At[m][k],acc[ai][bj][m][n],0,0,0); \
;     __builtin_amdgcn_s_setprio(0);}while(0)
;   #define WAIT_V(n) asm volatile("s_waitcnt vmcnt(" #n ")":::"memory")
;   #define WAIT_L(n) asm volatile("s_waitcnt lgkmcnt(" #n ")":::"memory")
;   #define BAR __builtin_amdgcn_s_barrier()
;   #define SCHED __builtin_amdgcn_sched_barrier(0)
; template <bool TWO, class MID> ...
;     ...
;     BAR; WAIT_L(0); MMA(1,0,At,B0); BAR; SCHED;
;     STAGE_B(SB(1,1),1,t+3);
;     WAIT_V(6); BAR; MMA(1,1,At,B1); BAR;
;   }
;   { LDB(B0,0,0); LDA(At,0,0); STAGE_A(SA(1,1),1,nt-1);
;     BAR; WAIT_L(0); MMA(0,0,At,B0); BAR;
;     LDB(B1,0,1); BAR; WAIT_L(0); MMA(0,1,At,B1); BAR;
	s_waitcnt lgkmcnt(0)
	s_setprio 1
	v_mfma_f32_16x16x32_bf16 v[62:65], v[166:169], v[182:185], v[62:65]
	v_mfma_f32_16x16x32_bf16 v[58:61], v[174:177], v[182:185], v[58:61]
	v_mfma_f32_16x16x32_bf16 v[54:57], v[166:169], v[190:193], v[54:57]
	v_mfma_f32_16x16x32_bf16 v[50:53], v[174:177], v[190:193], v[50:53]
	v_mfma_f32_16x16x32_bf16 v[46:49], v[166:169], v[200:203], v[46:49]
	v_mfma_f32_16x16x32_bf16 v[42:45], v[174:177], v[200:203], v[42:45]
	v_mfma_f32_16x16x32_bf16 v[38:41], v[166:169], v[208:211], v[38:41]
	v_mfma_f32_16x16x32_bf16 v[34:37], v[174:177], v[208:211], v[34:37]
	v_mfma_f32_16x16x32_bf16 v[62:65], v[170:173], v[186:189], v[62:65]
	v_mfma_f32_16x16x32_bf16 v[58:61], v[178:181], v[186:189], v[58:61]
	v_mfma_f32_16x16x32_bf16 v[54:57], v[170:173], v[196:199], v[54:57]
	v_mfma_f32_16x16x32_bf16 v[50:53], v[178:181], v[196:199], v[50:53]
	v_mfma_f32_16x16x32_bf16 v[46:49], v[170:173], v[204:207], v[46:49]
	v_mfma_f32_16x16x32_bf16 v[42:45], v[178:181], v[204:207], v[42:45]
	v_mfma_f32_16x16x32_bf16 v[38:41], v[170:173], v[212:215], v[38:41]
	v_mfma_f32_16x16x32_bf16 v[34:37], v[178:181], v[212:215], v[34:37]
	s_setprio 0
	s_barrier
	s_add_u32 s24, s25, 0x3480180
	s_addc_u32 s25, s26, 0
	v_readfirstlane_b32 s19, v144
	s_mov_b32 m0, s19
	global_load_lds_dwordx4 v132, s[24:25]
	v_readfirstlane_b32 s19, v146
	s_mov_b32 m0, s19
	global_load_lds_dwordx4 v130, s[24:25]
	s_waitcnt vmcnt(6)
	s_barrier
	s_setprio 1
	v_mfma_f32_16x16x32_bf16 v[30:33], v[216:219], v[182:185], v[30:33]
	v_mfma_f32_16x16x32_bf16 v[26:29], v[224:227], v[182:185], v[26:29]
	v_mfma_f32_16x16x32_bf16 v[22:25], v[216:219], v[190:193], v[22:25]
	v_mfma_f32_16x16x32_bf16 v[18:21], v[224:227], v[190:193], v[18:21]
	v_mfma_f32_16x16x32_bf16 v[14:17], v[216:219], v[200:203], v[14:17]
	v_mfma_f32_16x16x32_bf16 v[10:13], v[224:227], v[200:203], v[10:13]
	v_mfma_f32_16x16x32_bf16 v[6:9], v[216:219], v[208:211], v[6:9]
	v_mfma_f32_16x16x32_bf16 v[2:5], v[224:227], v[208:211], v[2:5]
	v_mfma_f32_16x16x32_bf16 v[30:33], v[220:223], v[186:189], v[30:33]
	v_mfma_f32_16x16x32_bf16 v[26:29], v[228:231], v[186:189], v[26:29]
	v_mfma_f32_16x16x32_bf16 v[22:25], v[220:223], v[196:199], v[22:25]
	v_mfma_f32_16x16x32_bf16 v[18:21], v[228:231], v[196:199], v[18:21]
	v_mfma_f32_16x16x32_bf16 v[14:17], v[220:223], v[204:207], v[14:17]
	v_mfma_f32_16x16x32_bf16 v[10:13], v[228:231], v[204:207], v[10:13]
	v_mfma_f32_16x16x32_bf16 v[6:9], v[220:223], v[212:215], v[6:9]
	v_mfma_f32_16x16x32_bf16 v[2:5], v[228:231], v[212:215], v[2:5]
	s_setprio 0
	s_add_i32 s18, s18, 2
	s_add_u32 s4, s4, 0x100
	s_addc_u32 s5, s5, 0
	s_cmp_lt_u32 s18, 28
	s_barrier
	s_cbranch_scc1 .LBB0_489
	ds_read_b128 v[152:155], v149
	ds_read_b128 v[156:159], v149 offset:1024
	ds_read_b128 v[160:163], v149 offset:2048
	ds_read_b128 v[164:167], v149 offset:3072
	ds_read_b128 v[168:171], v141
	ds_read_b128 v[172:175], v141 offset:1024
	ds_read_b128 v[176:179], v139
	ds_read_b128 v[180:183], v139 offset:1024
	ds_read_b128 v[184:187], v137
	ds_read_b128 v[188:191], v137 offset:1024
	ds_read_b128 v[196:199], v135
	ds_read_b128 v[200:203], v135 offset:1024
	s_add_u32 s4, s12, 0x80f80
	s_addc_u32 s5, s13, 0
	v_lshl_add_u64 v[132:133], s[4:5], 0, v[132:133]
	v_readfirstlane_b32 s12, v148
	s_mov_b32 m0, s12
	global_load_lds_dwordx4 v[132:133], off
	v_lshl_add_u64 v[130:131], s[4:5], 0, v[130:131]
	v_readfirstlane_b32 s4, v150
	s_mov_b32 m0, s4
	global_load_lds_dwordx4 v[130:131], off
	s_barrier
	s_waitcnt lgkmcnt(0)
	s_setprio 1
	v_mfma_f32_16x16x32_bf16 v[126:129], v[152:155], v[168:171], v[126:129]
	v_mfma_f32_16x16x32_bf16 v[122:125], v[160:163], v[168:171], v[122:125]
	v_mfma_f32_16x16x32_bf16 v[118:121], v[152:155], v[176:179], v[118:121]
	v_mfma_f32_16x16x32_bf16 v[114:117], v[160:163], v[176:179], v[114:117]
	v_mfma_f32_16x16x32_bf16 v[102:105], v[152:155], v[196:199], v[102:105]
	v_mfma_f32_16x16x32_bf16 v[98:101], v[160:163], v[196:199], v[98:101]
	v_mfma_f32_16x16x32_bf16 v[126:129], v[156:159], v[172:175], v[126:129]
	v_mfma_f32_16x16x32_bf16 v[122:125], v[164:167], v[172:175], v[122:125]
	v_mfma_f32_16x16x32_bf16 v[118:121], v[156:159], v[180:183], v[118:121]
	v_mfma_f32_16x16x32_bf16 v[114:117], v[164:167], v[180:183], v[114:117]
	v_mfma_f32_16x16x32_bf16 v[110:113], v[152:155], v[184:187], v[110:113]
	v_mfma_f32_16x16x32_bf16 v[106:109], v[160:163], v[184:187], v[106:109]
	v_mfma_f32_16x16x32_bf16 v[102:105], v[156:159], v[200:203], v[102:105]
	v_mfma_f32_16x16x32_bf16 v[98:101], v[164:167], v[200:203], v[98:101]
	v_mfma_f32_16x16x32_bf16 v[130:133], v[156:159], v[188:191], v[110:113]
	v_mfma_f32_16x16x32_bf16 v[148:151], v[164:167], v[188:191], v[106:109]
	s_setprio 0
	s_barrier
	s_nop 0
	ds_read_b128 v[106:109], v147
	ds_read_b128 v[110:113], v147 offset:1024
	ds_read_b128 v[204:207], v147 offset:2048
	ds_read_b128 v[208:211], v147 offset:3072
	s_barrier
	s_waitcnt lgkmcnt(0)
	s_setprio 1
	v_mfma_f32_16x16x32_bf16 v[86:89], v[106:109], v[176:179], v[86:89]
	v_mfma_f32_16x16x32_bf16 v[82:85], v[204:207], v[176:179], v[82:85]
	v_mfma_f32_16x16x32_bf16 v[70:73], v[106:109], v[196:199], v[70:73]
	v_mfma_f32_16x16x32_bf16 v[66:69], v[204:207], v[196:199], v[66:69]
	v_mfma_f32_16x16x32_bf16 v[94:97], v[106:109], v[168:171], v[94:97]
	v_mfma_f32_16x16x32_bf16 v[90:93], v[204:207], v[168:171], v[90:93]
	v_mfma_f32_16x16x32_bf16 v[86:89], v[110:113], v[180:183], v[86:89]
	v_mfma_f32_16x16x32_bf16 v[82:85], v[208:211], v[180:183], v[82:85]
	v_mfma_f32_16x16x32_bf16 v[78:81], v[106:109], v[184:187], v[78:81]
	v_mfma_f32_16x16x32_bf16 v[74:77], v[204:207], v[184:187], v[74:77]
	v_mfma_f32_16x16x32_bf16 v[70:73], v[110:113], v[200:203], v[70:73]
	v_mfma_f32_16x16x32_bf16 v[66:69], v[208:211], v[200:203], v[66:69]
	v_mfma_f32_16x16x32_bf16 v[212:215], v[110:113], v[172:175], v[94:97]
	v_mfma_f32_16x16x32_bf16 v[168:171], v[208:211], v[172:175], v[90:93]
	v_mfma_f32_16x16x32_bf16 v[172:175], v[110:113], v[188:191], v[78:81]
	v_mfma_f32_16x16x32_bf16 v[176:179], v[208:211], v[188:191], v[74:77]
	s_setprio 0
	s_barrier
;   #define LDA(dst,b,h) for(int m=0;m<4;++m)for(int k=0;k<2;++k) \
;     dst[m][k]=*reinterpret_cast<const bf16x8*>((char*)SA(b,h)+lds_byte(wr*64+m*16+fr,k*32+fq*8))
;   #define LDB(dst,b,h) for(int n=0;n<2;++n)for(int k=0;k<2;++k) \
;     dst[n][k]=*reinterpret_cast<const bf16x8*>((char*)SB(b,h)+lds_byte(wc*32+n*16+fr,k*32+fq*8))
;   #define MMA(ai,bj,At,Bt_) do{__builtin_amdgcn_s_setprio(1); \
;     for(int m=0;m<4;++m)for(int n=0;n<2;++n)for(int k=0;k<2;++k) \
;       acc[ai][bj][m][n]=__builtin_amdgcn_mfma_f32_16x16x32_bf16(Bt_[n][k],At[m][k],acc[ai][bj][m][n],0,0,0); \
;     __builtin_amdgcn_s_setprio(0);}while(0)
;   #define WAIT_V(n) asm volatile("s_waitcnt vmcnt(" #n ")":::"memory")
;   #define WAIT_L(n) asm volatile("s_waitcnt lgkmcnt(" #n ")":::"memory")
;   #define BAR __builtin_amdgcn_s_barrier()
; template <bool TWO, class MID> ...
;     ...
;     LDA(At,0,1); WAIT_V(4); BAR; WAIT_L(0); MMA(1,0,At,B0); MMA(1,1,At,B1); BAR; }
;   { LDB(B0,1,0); LDA(At,1,0); WAIT_V(2); BAR; WAIT_L(0); MMA(0,0,At,B0); BAR;
	s_nop 0
	ds_read_b128 v[74:77], v141 offset:16384
	ds_read_b128 v[78:81], v141 offset:17408
	ds_read_b128 v[90:93], v139 offset:16384
	ds_read_b128 v[94:97], v139 offset:17408
	ds_read_b128 v[180:183], v137 offset:16384
	ds_read_b128 v[184:187], v137 offset:17408
	ds_read_b128 v[188:191], v135 offset:16384
	ds_read_b128 v[196:199], v135 offset:17408
	s_waitcnt vmcnt(4)
	s_barrier
	s_waitcnt lgkmcnt(0)
	s_setprio 1
	v_mfma_f32_16x16x32_bf16 v[62:65], v[152:155], v[74:77], v[62:65]
	v_mfma_f32_16x16x32_bf16 v[58:61], v[160:163], v[74:77], v[58:61]
	v_mfma_f32_16x16x32_bf16 v[54:57], v[152:155], v[90:93], v[54:57]
	v_mfma_f32_16x16x32_bf16 v[50:53], v[160:163], v[90:93], v[50:53]
	v_mfma_f32_16x16x32_bf16 v[38:41], v[152:155], v[188:191], v[38:41]
	v_mfma_f32_16x16x32_bf16 v[34:37], v[160:163], v[188:191], v[34:37]
	v_mfma_f32_16x16x32_bf16 v[62:65], v[156:159], v[78:81], v[62:65]
	v_mfma_f32_16x16x32_bf16 v[58:61], v[164:167], v[78:81], v[58:61]
	v_mfma_f32_16x16x32_bf16 v[54:57], v[156:159], v[94:97], v[54:57]
	v_mfma_f32_16x16x32_bf16 v[50:53], v[164:167], v[94:97], v[50:53]
	v_mfma_f32_16x16x32_bf16 v[46:49], v[152:155], v[180:183], v[46:49]
	v_mfma_f32_16x16x32_bf16 v[42:45], v[160:163], v[180:183], v[42:45]
	v_mfma_f32_16x16x32_bf16 v[38:41], v[156:159], v[196:199], v[38:41]
	v_mfma_f32_16x16x32_bf16 v[34:37], v[164:167], v[196:199], v[34:37]
	v_mfma_f32_16x16x32_bf16 v[200:203], v[156:159], v[184:187], v[46:49]
	v_mfma_f32_16x16x32_bf16 v[216:219], v[164:167], v[184:187], v[42:45]
	s_setprio 0
	s_setprio 1
	v_mfma_f32_16x16x32_bf16 v[22:25], v[106:109], v[90:93], v[22:25]
	v_mfma_f32_16x16x32_bf16 v[18:21], v[204:207], v[90:93], v[18:21]
	v_mfma_f32_16x16x32_bf16 v[6:9], v[106:109], v[188:191], v[6:9]
	v_mfma_f32_16x16x32_bf16 v[2:5], v[204:207], v[188:191], v[2:5]
	v_mfma_f32_16x16x32_bf16 v[30:33], v[106:109], v[74:77], v[30:33]
	v_mfma_f32_16x16x32_bf16 v[26:29], v[204:207], v[74:77], v[26:29]
	v_mfma_f32_16x16x32_bf16 v[22:25], v[110:113], v[94:97], v[22:25]
	v_mfma_f32_16x16x32_bf16 v[18:21], v[208:211], v[94:97], v[18:21]
	v_mfma_f32_16x16x32_bf16 v[14:17], v[106:109], v[180:183], v[14:17]
	v_mfma_f32_16x16x32_bf16 v[10:13], v[204:207], v[180:183], v[10:13]
	v_mfma_f32_16x16x32_bf16 v[6:9], v[110:113], v[196:199], v[6:9]
	v_mfma_f32_16x16x32_bf16 v[2:5], v[208:211], v[196:199], v[2:5]
	v_mfma_f32_16x16x32_bf16 v[152:155], v[110:113], v[78:81], v[30:33]
	v_mfma_f32_16x16x32_bf16 v[156:159], v[208:211], v[78:81], v[26:29]
	v_mfma_f32_16x16x32_bf16 v[160:163], v[110:113], v[184:187], v[14:17]
	v_mfma_f32_16x16x32_bf16 v[164:167], v[208:211], v[184:187], v[10:13]
	s_setprio 0
	s_barrier
	s_nop 0
	ds_read_b128 v[10:13], v145
	ds_read_b128 v[14:17], v145 offset:1024
	ds_read_b128 v[180:183], v145 offset:2048
	ds_read_b128 v[144:147], v145 offset:3072
	ds_read_b128 v[26:29], v141 offset:32768
	ds_read_b128 v[30:33], v141 offset:33792
	ds_read_b128 v[42:45], v139 offset:32768
	ds_read_b128 v[46:49], v139 offset:33792
	ds_read_b128 v[184:187], v137 offset:32768
	ds_read_b128 v[188:191], v137 offset:33792
	ds_read_b128 v[196:199], v135 offset:32768
	ds_read_b128 v[204:207], v135 offset:33792
	s_waitcnt vmcnt(2)
	s_barrier
	s_waitcnt lgkmcnt(0)
	s_setprio 1
	v_mfma_f32_16x16x32_bf16 v[74:77], v[10:13], v[26:29], v[126:129]
	v_mfma_f32_16x16x32_bf16 v[126:129], v[14:17], v[30:33], v[74:77]
	v_mfma_f32_16x16x32_bf16 v[74:77], v[180:183], v[26:29], v[122:125]
	v_mfma_f32_16x16x32_bf16 v[122:125], v[144:147], v[30:33], v[74:77]
	v_mfma_f32_16x16x32_bf16 v[74:77], v[10:13], v[42:45], v[118:121]
	v_mfma_f32_16x16x32_bf16 v[110:113], v[14:17], v[46:49], v[74:77]
	v_mfma_f32_16x16x32_bf16 v[74:77], v[180:183], v[42:45], v[114:117]
	v_mfma_f32_16x16x32_bf16 v[106:109], v[144:147], v[46:49], v[74:77]
	v_mfma_f32_16x16x32_bf16 v[74:77], v[10:13], v[184:187], v[130:133]
	v_mfma_f32_16x16x32_bf16 v[94:97], v[14:17], v[188:191], v[74:77]
	v_mfma_f32_16x16x32_bf16 v[74:77], v[180:183], v[184:187], v[148:151]
	v_mfma_f32_16x16x32_bf16 v[90:93], v[144:147], v[188:191], v[74:77]
	v_mfma_f32_16x16x32_bf16 v[74:77], v[10:13], v[196:199], v[102:105]
	v_mfma_f32_16x16x32_bf16 v[78:81], v[14:17], v[204:207], v[74:77]
	v_mfma_f32_16x16x32_bf16 v[74:77], v[180:183], v[196:199], v[98:101]
	v_mfma_f32_16x16x32_bf16 v[74:77], v[144:147], v[204:207], v[74:77]
	s_setprio 0
	s_barrier
;   #define LDA(dst,b,h) for(int m=0;m<4;++m)for(int k=0;k<2;++k) \
;     dst[m][k]=*reinterpret_cast<const bf16x8*>((char*)SA(b,h)+lds_byte(wr*64+m*16+fr,k*32+fq*8))
;   #define LDB(dst,b,h) for(int n=0;n<2;++n)for(int k=0;k<2;++k) \
;     dst[n][k]=*reinterpret_cast<const bf16x8*>((char*)SB(b,h)+lds_byte(wc*32+n*16+fr,k*32+fq*8))
;   #define MMA(ai,bj,At,Bt_) do{__builtin_amdgcn_s_setprio(1); \
;     for(int m=0;m<4;++m)for(int n=0;n<2;++n)for(int k=0;k<2;++k) \
;       acc[ai][bj][m][n]=__builtin_amdgcn_mfma_f32_16x16x32_bf16(Bt_[n][k],At[m][k],acc[ai][bj][m][n],0,0,0); \
;     __builtin_amdgcn_s_setprio(0);}while(0)
;   #define WAIT_V(n) asm volatile("s_waitcnt vmcnt(" #n ")":::"memory")
;   #define WAIT_L(n) asm volatile("s_waitcnt lgkmcnt(" #n ")":::"memory")
;   #define BAR __builtin_amdgcn_s_barrier()
; template <bool TWO, class MID> ...
;     ...
;     LDB(B1,1,1); WAIT_V(0); BAR; WAIT_L(0); MMA(0,1,At,B1); BAR;
;     LDA(At,1,1); BAR; WAIT_L(0); MMA(1,0,At,B0); MMA(1,1,At,B1); BAR; }
;   if(wr==0)BAR;
	ds_read_b128 v[130:133], v143
	ds_read_b128 v[148:151], v143 offset:1024
	ds_read_b128 v[208:211], v143 offset:2048
	ds_read_b128 v[220:223], v143 offset:3072
	s_waitcnt vmcnt(0)
	s_barrier
	s_waitcnt lgkmcnt(0)
	s_setprio 1
	v_mfma_f32_16x16x32_bf16 v[98:101], v[130:133], v[26:29], v[212:215]
	v_mfma_f32_16x16x32_bf16 v[26:29], v[208:211], v[26:29], v[168:171]
	v_mfma_f32_16x16x32_bf16 v[114:117], v[220:223], v[30:33], v[26:29]
	v_mfma_f32_16x16x32_bf16 v[26:29], v[130:133], v[42:45], v[86:89]
	v_mfma_f32_16x16x32_bf16 v[102:105], v[148:151], v[46:49], v[26:29]
	v_mfma_f32_16x16x32_bf16 v[26:29], v[208:211], v[42:45], v[82:85]
	v_mfma_f32_16x16x32_bf16 v[118:121], v[148:151], v[30:33], v[98:101]
	v_mfma_f32_16x16x32_bf16 v[98:101], v[220:223], v[46:49], v[26:29]
	v_mfma_f32_16x16x32_bf16 v[26:29], v[130:133], v[184:187], v[172:175]
	v_mfma_f32_16x16x32_bf16 v[86:89], v[148:151], v[188:191], v[26:29]
	v_mfma_f32_16x16x32_bf16 v[26:29], v[208:211], v[184:187], v[176:179]
	v_mfma_f32_16x16x32_bf16 v[82:85], v[220:223], v[188:191], v[26:29]
	v_mfma_f32_16x16x32_bf16 v[26:29], v[130:133], v[196:199], v[70:73]
	v_mfma_f32_16x16x32_bf16 v[70:73], v[148:151], v[204:207], v[26:29]
	v_mfma_f32_16x16x32_bf16 v[26:29], v[208:211], v[196:199], v[66:69]
	v_mfma_f32_16x16x32_bf16 v[66:69], v[220:223], v[204:207], v[26:29]
	s_setprio 0
	s_barrier
	ds_read_b128 v[168:171], v141 offset:49152
	ds_read_b128 v[140:143], v141 offset:50176
	ds_read_b128 v[172:175], v139 offset:49152
	ds_read_b128 v[176:179], v139 offset:50176
	ds_read_b128 v[184:187], v137 offset:49152
	ds_read_b128 v[136:139], v137 offset:50176
	ds_read_b128 v[188:191], v135 offset:49152
	ds_read_b128 v[196:199], v135 offset:50176
	s_barrier
	s_waitcnt lgkmcnt(0)
	s_setprio 1
	v_mfma_f32_16x16x32_bf16 v[26:29], v[10:13], v[168:171], v[62:65]
	v_mfma_f32_16x16x32_bf16 v[62:65], v[14:17], v[140:143], v[26:29]
	v_mfma_f32_16x16x32_bf16 v[26:29], v[180:183], v[168:171], v[58:61]
	v_mfma_f32_16x16x32_bf16 v[58:61], v[144:147], v[140:143], v[26:29]
	v_mfma_f32_16x16x32_bf16 v[26:29], v[10:13], v[172:175], v[54:57]
	v_mfma_f32_16x16x32_bf16 v[46:49], v[14:17], v[176:179], v[26:29]
	v_mfma_f32_16x16x32_bf16 v[26:29], v[180:183], v[172:175], v[50:53]
	v_mfma_f32_16x16x32_bf16 v[42:45], v[144:147], v[176:179], v[26:29]
	v_mfma_f32_16x16x32_bf16 v[26:29], v[10:13], v[184:187], v[200:203]
	v_mfma_f32_16x16x32_bf16 v[10:13], v[10:13], v[188:191], v[38:41]
	v_mfma_f32_16x16x32_bf16 v[30:33], v[14:17], v[136:139], v[26:29]
	v_mfma_f32_16x16x32_bf16 v[26:29], v[180:183], v[184:187], v[216:219]
	v_mfma_f32_16x16x32_bf16 v[14:17], v[14:17], v[196:199], v[10:13]
	v_mfma_f32_16x16x32_bf16 v[10:13], v[180:183], v[188:191], v[34:37]
	v_mfma_f32_16x16x32_bf16 v[26:29], v[144:147], v[136:139], v[26:29]
	v_mfma_f32_16x16x32_bf16 v[10:13], v[144:147], v[196:199], v[10:13]
	s_setprio 0
	s_setprio 1
	v_mfma_f32_16x16x32_bf16 v[34:37], v[130:133], v[168:171], v[152:155]
	v_mfma_f32_16x16x32_bf16 v[54:57], v[148:151], v[140:143], v[34:37]
	v_mfma_f32_16x16x32_bf16 v[34:37], v[208:211], v[168:171], v[156:159]
	v_mfma_f32_16x16x32_bf16 v[18:21], v[208:211], v[172:175], v[18:21]
	v_mfma_f32_16x16x32_bf16 v[50:53], v[220:223], v[140:143], v[34:37]
	v_mfma_f32_16x16x32_bf16 v[22:25], v[130:133], v[172:175], v[22:25]
	v_mfma_f32_16x16x32_bf16 v[34:37], v[220:223], v[176:179], v[18:21]
	v_mfma_f32_16x16x32_bf16 v[18:21], v[130:133], v[184:187], v[160:163]
	v_mfma_f32_16x16x32_bf16 v[38:41], v[148:151], v[176:179], v[22:25]
	v_mfma_f32_16x16x32_bf16 v[22:25], v[148:151], v[136:139], v[18:21]
	v_mfma_f32_16x16x32_bf16 v[18:21], v[208:211], v[184:187], v[164:167]
	v_mfma_f32_16x16x32_bf16 v[6:9], v[130:133], v[188:191], v[6:9]
	v_mfma_f32_16x16x32_bf16 v[2:5], v[208:211], v[188:191], v[2:5]
	v_mfma_f32_16x16x32_bf16 v[18:21], v[220:223], v[136:139], v[18:21]
	v_mfma_f32_16x16x32_bf16 v[6:9], v[148:151], v[196:199], v[6:9]
	v_mfma_f32_16x16x32_bf16 v[2:5], v[220:223], v[196:199], v[2:5]
	s_setprio 0
	v_cmp_gt_u32_e32 vcc, s30, v1
	s_barrier
	s_and_saveexec_b64 s[4:5], vcc
	s_cbranch_execz .LBB0_492
	s_barrier

;   #define LDA(dst,b,h) for(int m=0;m<4;++m)for(int k=0;k<2;++k) \
;     dst[m][k]=*reinterpret_cast<const bf16x8*>((char*)SA(b,h)+lds_byte(wr*64+m*16+fr,k*32+fq*8))
;   #define LDB(dst,b,h) for(int n=0;n<2;++n)for(int k=0;k<2;++k) \
;     dst[n][k]=*reinterpret_cast<const bf16x8*>((char*)SB(b,h)+lds_byte(wc*32+n*16+fr,k*32+fq*8))
;   #define MMA(ai,bj,At,Bt_) do{__builtin_amdgcn_s_setprio(1); \
;     for(int m=0;m<4;++m)for(int n=0;n<2;++n)for(int k=0;k<2;++k) \
;       acc[ai][bj][m][n]=__builtin_amdgcn_mfma_f32_16x16x32_bf16(Bt_[n][k],At[m][k],acc[ai][bj][m][n],0,0,0); \
;     __builtin_amdgcn_s_setprio(0);}while(0)
;   #define WAIT_V(n) asm volatile("s_waitcnt vmcnt(" #n ")":::"memory")
;   #define WAIT_L(n) asm volatile("s_waitcnt lgkmcnt(" #n ")":::"memory")
;   #define BAR __builtin_amdgcn_s_barrier()
;   #define SCHED __builtin_amdgcn_sched_barrier(0)
; __device__ __forceinline__ void gll16(const void* g, const void* l) {
;   const unsigned m = __builtin_amdgcn_readfirstlane((unsigned)(uintptr_t)l);
;   asm volatile("s_mov_b32 m0, %0\n\tglobal_load_lds_dwordx4 %1, off" :: "s"(m), "v"(g) : "memory");
; }
; template <bool TWO, class MID> ...
;     ...
;     LDB(B0,0,0); SCHED; LDA(At,0,0); STAGE_A(SA(1,1),1,t+1);
;     WAIT_L(8); BAR; WAIT_L(0); MMA(0,0,At,B0); BAR; SCHED;
;     LDB(B1,0,1); STAGE_B(SB(0,0),0,t+2);
;     BAR; WAIT_L(0); MMA(0,1,At,B1); BAR;
;     LDA(At,0,1); STAGE_A(SA(0,0),0,t+2);
;     BAR; WAIT_L(0); MMA(1,0,At,B0); BAR; SCHED;
;     STAGE_B(SB(0,1),1,t+2);
;     WAIT_V(6); BAR; MMA(1,1,At,B1); BAR;
.LBB0_562:
	ds_read_b128 v[166:169], v149
	ds_read_b128 v[170:173], v149 offset:1024
	ds_read_b128 v[174:177], v149 offset:2048
	ds_read_b128 v[178:181], v149 offset:3072
	ds_read_b128 v[182:185], v141
	ds_read_b128 v[186:189], v141 offset:1024
	ds_read_b128 v[190:193], v139
	ds_read_b128 v[196:199], v139 offset:1024
	ds_read_b128 v[200:203], v137
	ds_read_b128 v[204:207], v137 offset:1024
	ds_read_b128 v[208:211], v135
	ds_read_b128 v[212:215], v135 offset:1024
	s_add_u32 s23, s4, s12
	s_addc_u32 s24, s5, s13
	s_add_u32 s26, s23, 0x8080080
	s_addc_u32 s27, s24, 0
	v_readfirstlane_b32 s25, v148
	s_mov_b32 m0, s25
	global_load_lds_dwordx4 v132, s[26:27]
	v_readfirstlane_b32 s25, v150
	s_mov_b32 m0, s25
	global_load_lds_dwordx4 v130, s[26:27]
	s_waitcnt lgkmcnt(8)
	s_barrier
	s_waitcnt lgkmcnt(0)
	s_setprio 1
	v_mfma_f32_16x16x32_bf16 v[126:129], v[166:169], v[182:185], v[126:129]
	v_mfma_f32_16x16x32_bf16 v[122:125], v[174:177], v[182:185], v[122:125]
	v_mfma_f32_16x16x32_bf16 v[118:121], v[166:169], v[190:193], v[118:121]
	v_mfma_f32_16x16x32_bf16 v[114:117], v[174:177], v[190:193], v[114:117]
	v_mfma_f32_16x16x32_bf16 v[110:113], v[166:169], v[200:203], v[110:113]
	v_mfma_f32_16x16x32_bf16 v[106:109], v[174:177], v[200:203], v[106:109]
	v_mfma_f32_16x16x32_bf16 v[102:105], v[166:169], v[208:211], v[102:105]
	v_mfma_f32_16x16x32_bf16 v[98:101], v[174:177], v[208:211], v[98:101]
	v_mfma_f32_16x16x32_bf16 v[126:129], v[170:173], v[186:189], v[126:129]
	v_mfma_f32_16x16x32_bf16 v[122:125], v[178:181], v[186:189], v[122:125]
	v_mfma_f32_16x16x32_bf16 v[118:121], v[170:173], v[196:199], v[118:121]
	v_mfma_f32_16x16x32_bf16 v[114:117], v[178:181], v[196:199], v[114:117]
	v_mfma_f32_16x16x32_bf16 v[110:113], v[170:173], v[204:207], v[110:113]
	v_mfma_f32_16x16x32_bf16 v[106:109], v[178:181], v[204:207], v[106:109]
	v_mfma_f32_16x16x32_bf16 v[102:105], v[170:173], v[212:215], v[102:105]
	v_mfma_f32_16x16x32_bf16 v[98:101], v[178:181], v[212:215], v[98:101]
	s_setprio 0
	s_barrier
	s_add_u32 s25, s4, s14
	ds_read_b128 v[216:219], v147
	ds_read_b128 v[220:223], v147 offset:1024
	ds_read_b128 v[224:227], v147 offset:2048
	ds_read_b128 v[228:231], v147 offset:3072
	s_addc_u32 s26, s5, s15
	s_add_u32 s28, s25, 0x3c00100
	s_addc_u32 s29, s26, 0
	v_readfirstlane_b32 s27, v152
	s_mov_b32 m0, s27
	global_load_lds_dwordx4 v132, s[28:29]
	v_readfirstlane_b32 s27, v154
	s_mov_b32 m0, s27
	global_load_lds_dwordx4 v130, s[28:29]
	s_barrier
	s_waitcnt lgkmcnt(0)
	s_setprio 1
	v_mfma_f32_16x16x32_bf16 v[94:97], v[216:219], v[182:185], v[94:97]
	v_mfma_f32_16x16x32_bf16 v[90:93], v[224:227], v[182:185], v[90:93]
	v_mfma_f32_16x16x32_bf16 v[86:89], v[216:219], v[190:193], v[86:89]
	v_mfma_f32_16x16x32_bf16 v[82:85], v[224:227], v[190:193], v[82:85]
	v_mfma_f32_16x16x32_bf16 v[78:81], v[216:219], v[200:203], v[78:81]
	v_mfma_f32_16x16x32_bf16 v[74:77], v[224:227], v[200:203], v[74:77]
	v_mfma_f32_16x16x32_bf16 v[70:73], v[216:219], v[208:211], v[70:73]
	v_mfma_f32_16x16x32_bf16 v[66:69], v[224:227], v[208:211], v[66:69]
	v_mfma_f32_16x16x32_bf16 v[94:97], v[220:223], v[186:189], v[94:97]
	v_mfma_f32_16x16x32_bf16 v[90:93], v[228:231], v[186:189], v[90:93]
	v_mfma_f32_16x16x32_bf16 v[86:89], v[220:223], v[196:199], v[86:89]
	v_mfma_f32_16x16x32_bf16 v[82:85], v[228:231], v[196:199], v[82:85]
	v_mfma_f32_16x16x32_bf16 v[78:81], v[220:223], v[204:207], v[78:81]
	v_mfma_f32_16x16x32_bf16 v[74:77], v[228:231], v[204:207], v[74:77]
	v_mfma_f32_16x16x32_bf16 v[70:73], v[220:223], v[212:215], v[70:73]
	v_mfma_f32_16x16x32_bf16 v[66:69], v[228:231], v[212:215], v[66:69]
	s_setprio 0
	s_barrier
	ds_read_b128 v[182:185], v141 offset:16384
	ds_read_b128 v[186:189], v141 offset:17408
	ds_read_b128 v[190:193], v139 offset:16384
	ds_read_b128 v[196:199], v139 offset:17408
	ds_read_b128 v[200:203], v137 offset:16384
	ds_read_b128 v[204:207], v137 offset:17408
	ds_read_b128 v[208:211], v135 offset:16384
	ds_read_b128 v[212:215], v135 offset:17408
	s_add_u32 s28, s23, 0x8000100
	s_addc_u32 s29, s24, 0
	v_readfirstlane_b32 s27, v138
	s_mov_b32 m0, s27
	global_load_lds_dwordx4 v132, s[28:29]
	v_readfirstlane_b32 s27, v156
	s_mov_b32 m0, s27
	global_load_lds_dwordx4 v130, s[28:29]
	s_barrier
	s_waitcnt lgkmcnt(0)
	s_setprio 1
	v_mfma_f32_16x16x32_bf16 v[62:65], v[166:169], v[182:185], v[62:65]
	v_mfma_f32_16x16x32_bf16 v[58:61], v[174:177], v[182:185], v[58:61]
	v_mfma_f32_16x16x32_bf16 v[54:57], v[166:169], v[190:193], v[54:57]
	v_mfma_f32_16x16x32_bf16 v[50:53], v[174:177], v[190:193], v[50:53]
	v_mfma_f32_16x16x32_bf16 v[46:49], v[166:169], v[200:203], v[46:49]
	v_mfma_f32_16x16x32_bf16 v[42:45], v[174:177], v[200:203], v[42:45]
	v_mfma_f32_16x16x32_bf16 v[38:41], v[166:169], v[208:211], v[38:41]
	v_mfma_f32_16x16x32_bf16 v[34:37], v[174:177], v[208:211], v[34:37]
	v_mfma_f32_16x16x32_bf16 v[62:65], v[170:173], v[186:189], v[62:65]
	v_mfma_f32_16x16x32_bf16 v[58:61], v[178:181], v[186:189], v[58:61]
	v_mfma_f32_16x16x32_bf16 v[54:57], v[170:173], v[196:199], v[54:57]
	v_mfma_f32_16x16x32_bf16 v[50:53], v[178:181], v[196:199], v[50:53]
	v_mfma_f32_16x16x32_bf16 v[46:49], v[170:173], v[204:207], v[46:49]
	v_mfma_f32_16x16x32_bf16 v[42:45], v[178:181], v[204:207], v[42:45]
	v_mfma_f32_16x16x32_bf16 v[38:41], v[170:173], v[212:215], v[38:41]
	v_mfma_f32_16x16x32_bf16 v[34:37], v[178:181], v[212:215], v[34:37]
	s_setprio 0
	s_barrier
	s_add_u32 s28, s25, 0x3c80100
	s_addc_u32 s29, s26, 0
	v_readfirstlane_b32 s27, v158
	s_mov_b32 m0, s27
	global_load_lds_dwordx4 v132, s[28:29]
	v_readfirstlane_b32 s27, v160
	s_mov_b32 m0, s27
	global_load_lds_dwordx4 v130, s[28:29]
	s_waitcnt vmcnt(6)
	s_barrier
;   #define LDA(dst,b,h) for(int m=0;m<4;++m)for(int k=0;k<2;++k) \
;     dst[m][k]=*reinterpret_cast<const bf16x8*>((char*)SA(b,h)+lds_byte(wr*64+m*16+fr,k*32+fq*8))
;   #define LDB(dst,b,h) for(int n=0;n<2;++n)for(int k=0;k<2;++k) \
;     dst[n][k]=*reinterpret_cast<const bf16x8*>((char*)SB(b,h)+lds_byte(wc*32+n*16+fr,k*32+fq*8))
;   #define MMA(ai,bj,At,Bt_) do{__builtin_amdgcn_s_setprio(1); \
;     for(int m=0;m<4;++m)for(int n=0;n<2;++n)for(int k=0;k<2;++k) \
;       acc[ai][bj][m][n]=__builtin_amdgcn_mfma_f32_16x16x32_bf16(Bt_[n][k],At[m][k],acc[ai][bj][m][n],0,0,0); \
;     __builtin_amdgcn_s_setprio(0);}while(0)
;   #define WAIT_V(n) asm volatile("s_waitcnt vmcnt(" #n ")":::"memory")
;   #define WAIT_L(n) asm volatile("s_waitcnt lgkmcnt(" #n ")":::"memory")
;   #define BAR __builtin_amdgcn_s_barrier()
;   #define SCHED __builtin_amdgcn_sched_barrier(0)
; __device__ __forceinline__ void gll16(const void* g, const void* l) {
;   const unsigned m = __builtin_amdgcn_readfirstlane((unsigned)(uintptr_t)l);
;   asm volatile("s_mov_b32 m0, %0\n\tglobal_load_lds_dwordx4 %1, off" :: "s"(m), "v"(g) : "memory");
; }
; template <bool TWO, class MID> ...
;     ...
;     WAIT_V(6); BAR; MMA(1,1,At,B1); BAR;
;     LDB(B0,1,0); SCHED; LDA(At,1,0); STAGE_A(SA(0,1),1,t+2);
;     WAIT_L(8); BAR; WAIT_L(0); MMA(0,0,At,B0); BAR; SCHED;
;     LDB(B1,1,1); STAGE_B(SB(1,0),0,t+3);
;     BAR; WAIT_L(0); MMA(0,1,At,B1); BAR;
;     LDA(At,1,1); STAGE_A(SA(1,0),0,t+3);
	s_setprio 1
	v_mfma_f32_16x16x32_bf16 v[30:33], v[216:219], v[182:185], v[30:33]
	v_mfma_f32_16x16x32_bf16 v[26:29], v[224:227], v[182:185], v[26:29]
	v_mfma_f32_16x16x32_bf16 v[22:25], v[216:219], v[190:193], v[22:25]
	v_mfma_f32_16x16x32_bf16 v[18:21], v[224:227], v[190:193], v[18:21]
	v_mfma_f32_16x16x32_bf16 v[14:17], v[216:219], v[200:203], v[14:17]
	v_mfma_f32_16x16x32_bf16 v[10:13], v[224:227], v[200:203], v[10:13]
	v_mfma_f32_16x16x32_bf16 v[6:9], v[216:219], v[208:211], v[6:9]
	v_mfma_f32_16x16x32_bf16 v[2:5], v[224:227], v[208:211], v[2:5]
	v_mfma_f32_16x16x32_bf16 v[30:33], v[220:223], v[186:189], v[30:33]
	v_mfma_f32_16x16x32_bf16 v[26:29], v[228:231], v[186:189], v[26:29]
	v_mfma_f32_16x16x32_bf16 v[22:25], v[220:223], v[196:199], v[22:25]
	v_mfma_f32_16x16x32_bf16 v[18:21], v[228:231], v[196:199], v[18:21]
	v_mfma_f32_16x16x32_bf16 v[14:17], v[220:223], v[204:207], v[14:17]
	v_mfma_f32_16x16x32_bf16 v[10:13], v[228:231], v[204:207], v[10:13]
	v_mfma_f32_16x16x32_bf16 v[6:9], v[220:223], v[212:215], v[6:9]
	v_mfma_f32_16x16x32_bf16 v[2:5], v[228:231], v[212:215], v[2:5]
	s_setprio 0
	s_barrier
	ds_read_b128 v[166:169], v145
	ds_read_b128 v[170:173], v145 offset:1024
	ds_read_b128 v[174:177], v145 offset:2048
	ds_read_b128 v[178:181], v145 offset:3072
	ds_read_b128 v[182:185], v141 offset:32768
	ds_read_b128 v[186:189], v141 offset:33792
	ds_read_b128 v[190:193], v139 offset:32768
	ds_read_b128 v[196:199], v139 offset:33792
	ds_read_b128 v[200:203], v137 offset:32768
	ds_read_b128 v[204:207], v137 offset:33792
	ds_read_b128 v[208:211], v135 offset:32768
	ds_read_b128 v[212:215], v135 offset:33792
	s_add_u32 s28, s23, 0x8080100
	s_addc_u32 s29, s24, 0
	v_readfirstlane_b32 s27, v162
	s_mov_b32 m0, s27
	global_load_lds_dwordx4 v132, s[28:29]
	v_readfirstlane_b32 s27, v164
	s_mov_b32 m0, s27
	global_load_lds_dwordx4 v130, s[28:29]
	s_waitcnt lgkmcnt(8)
	s_barrier
	s_waitcnt lgkmcnt(0)
	s_setprio 1
	v_mfma_f32_16x16x32_bf16 v[126:129], v[166:169], v[182:185], v[126:129]
	v_mfma_f32_16x16x32_bf16 v[122:125], v[174:177], v[182:185], v[122:125]
	v_mfma_f32_16x16x32_bf16 v[118:121], v[166:169], v[190:193], v[118:121]
	v_mfma_f32_16x16x32_bf16 v[114:117], v[174:177], v[190:193], v[114:117]
	v_mfma_f32_16x16x32_bf16 v[110:113], v[166:169], v[200:203], v[110:113]
	v_mfma_f32_16x16x32_bf16 v[106:109], v[174:177], v[200:203], v[106:109]
	v_mfma_f32_16x16x32_bf16 v[102:105], v[166:169], v[208:211], v[102:105]
	v_mfma_f32_16x16x32_bf16 v[98:101], v[174:177], v[208:211], v[98:101]
	v_mfma_f32_16x16x32_bf16 v[126:129], v[170:173], v[186:189], v[126:129]
	v_mfma_f32_16x16x32_bf16 v[122:125], v[178:181], v[186:189], v[122:125]
	v_mfma_f32_16x16x32_bf16 v[118:121], v[170:173], v[196:199], v[118:121]
	v_mfma_f32_16x16x32_bf16 v[114:117], v[178:181], v[196:199], v[114:117]
	v_mfma_f32_16x16x32_bf16 v[110:113], v[170:173], v[204:207], v[110:113]
	v_mfma_f32_16x16x32_bf16 v[106:109], v[178:181], v[204:207], v[106:109]
	v_mfma_f32_16x16x32_bf16 v[102:105], v[170:173], v[212:215], v[102:105]
	v_mfma_f32_16x16x32_bf16 v[98:101], v[178:181], v[212:215], v[98:101]
	s_setprio 0
	s_barrier
	ds_read_b128 v[216:219], v143
	ds_read_b128 v[220:223], v143 offset:1024
	ds_read_b128 v[224:227], v143 offset:2048
	ds_read_b128 v[228:231], v143 offset:3072
	s_add_u32 s28, s25, 0x3c00180
	s_addc_u32 s29, s26, 0
	v_readfirstlane_b32 s27, v134
	s_mov_b32 m0, s27
	global_load_lds_dwordx4 v132, s[28:29]
	v_readfirstlane_b32 s27, v136
	s_mov_b32 m0, s27
	global_load_lds_dwordx4 v130, s[28:29]
	s_barrier
	s_waitcnt lgkmcnt(0)
	s_setprio 1
	v_mfma_f32_16x16x32_bf16 v[94:97], v[216:219], v[182:185], v[94:97]
	v_mfma_f32_16x16x32_bf16 v[90:93], v[224:227], v[182:185], v[90:93]
	v_mfma_f32_16x16x32_bf16 v[86:89], v[216:219], v[190:193], v[86:89]
	v_mfma_f32_16x16x32_bf16 v[82:85], v[224:227], v[190:193], v[82:85]
	v_mfma_f32_16x16x32_bf16 v[78:81], v[216:219], v[200:203], v[78:81]
	v_mfma_f32_16x16x32_bf16 v[74:77], v[224:227], v[200:203], v[74:77]
	v_mfma_f32_16x16x32_bf16 v[70:73], v[216:219], v[208:211], v[70:73]
	v_mfma_f32_16x16x32_bf16 v[66:69], v[224:227], v[208:211], v[66:69]
	v_mfma_f32_16x16x32_bf16 v[94:97], v[220:223], v[186:189], v[94:97]
	v_mfma_f32_16x16x32_bf16 v[90:93], v[228:231], v[186:189], v[90:93]
	v_mfma_f32_16x16x32_bf16 v[86:89], v[220:223], v[196:199], v[86:89]
	v_mfma_f32_16x16x32_bf16 v[82:85], v[228:231], v[196:199], v[82:85]
	v_mfma_f32_16x16x32_bf16 v[78:81], v[220:223], v[204:207], v[78:81]
	v_mfma_f32_16x16x32_bf16 v[74:77], v[228:231], v[204:207], v[74:77]
	v_mfma_f32_16x16x32_bf16 v[70:73], v[220:223], v[212:215], v[70:73]
	v_mfma_f32_16x16x32_bf16 v[66:69], v[228:231], v[212:215], v[66:69]
	s_setprio 0
	s_barrier
	ds_read_b128 v[182:185], v141 offset:49152
	ds_read_b128 v[186:189], v141 offset:50176
	ds_read_b128 v[190:193], v139 offset:49152
	ds_read_b128 v[196:199], v139 offset:50176
	ds_read_b128 v[200:203], v137 offset:49152
	ds_read_b128 v[204:207], v137 offset:50176
	ds_read_b128 v[208:211], v135 offset:49152
	ds_read_b128 v[212:215], v135 offset:50176
	s_add_u32 s28, s23, 0x8000180
	s_addc_u32 s29, s24, 0
	v_readfirstlane_b32 s23, v140
	s_mov_b32 m0, s23
	global_load_lds_dwordx4 v132, s[28:29]
	v_readfirstlane_b32 s23, v142
	s_mov_b32 m0, s23
	global_load_lds_dwordx4 v130, s[28:29]
	s_barrier
;   #define LDA(dst,b,h) for(int m=0;m<4;++m)for(int k=0;k<2;++k) \
;     dst[m][k]=*reinterpret_cast<const bf16x8*>((char*)SA(b,h)+lds_byte(wr*64+m*16+fr,k*32+fq*8))
;   #define LDB(dst,b,h) for(int n=0;n<2;++n)for(int k=0;k<2;++k) \
;     dst[n][k]=*reinterpret_cast<const bf16x8*>((char*)SB(b,h)+lds_byte(wc*32+n*16+fr,k*32+fq*8))
;   #define MMA(ai,bj,At,Bt_) do{__builtin_amdgcn_s_setprio(1); \
;     for(int m=0;m<4;++m)for(int n=0;n<2;++n)for(int k=0;k<2;++k) \
;       acc[ai][bj][m][n]=__builtin_amdgcn_mfma_f32_16x16x32_bf16(Bt_[n][k],At[m][k],acc[ai][bj][m][n],0,0,0); \
;     __builtin_amdgcn_s_setprio(0);}while(0)
;   #define WAIT_V(n) asm volatile("s_waitcnt vmcnt(" #n ")":::"memory")
;   #define WAIT_L(n) asm volatile("s_waitcnt lgkmcnt(" #n ")":::"memory")
;   #define BAR __builtin_amdgcn_s_barrier()
;   #define SCHED __builtin_amdgcn_sched_barrier(0)
; template <bool TWO, class MID> ...
;     ...
;     BAR; WAIT_L(0); MMA(1,0,At,B0); BAR; SCHED;
;     STAGE_B(SB(1,1),1,t+3);
;     WAIT_V(6); BAR; MMA(1,1,At,B1); BAR;
;   }
;   { LDB(B0,0,0); LDA(At,0,0); STAGE_A(SA(1,1),1,nt-1);
;     BAR; WAIT_L(0); MMA(0,0,At,B0); BAR;
;     LDB(B1,0,1); BAR; WAIT_L(0); MMA(0,1,At,B1); BAR;
	s_waitcnt lgkmcnt(0)
	s_setprio 1
	v_mfma_f32_16x16x32_bf16 v[62:65], v[166:169], v[182:185], v[62:65]
	v_mfma_f32_16x16x32_bf16 v[58:61], v[174:177], v[182:185], v[58:61]
	v_mfma_f32_16x16x32_bf16 v[54:57], v[166:169], v[190:193], v[54:57]
	v_mfma_f32_16x16x32_bf16 v[50:53], v[174:177], v[190:193], v[50:53]
	v_mfma_f32_16x16x32_bf16 v[46:49], v[166:169], v[200:203], v[46:49]
	v_mfma_f32_16x16x32_bf16 v[42:45], v[174:177], v[200:203], v[42:45]
	v_mfma_f32_16x16x32_bf16 v[38:41], v[166:169], v[208:211], v[38:41]
	v_mfma_f32_16x16x32_bf16 v[34:37], v[174:177], v[208:211], v[34:37]
	v_mfma_f32_16x16x32_bf16 v[62:65], v[170:173], v[186:189], v[62:65]
	v_mfma_f32_16x16x32_bf16 v[58:61], v[178:181], v[186:189], v[58:61]
	v_mfma_f32_16x16x32_bf16 v[54:57], v[170:173], v[196:199], v[54:57]
	v_mfma_f32_16x16x32_bf16 v[50:53], v[178:181], v[196:199], v[50:53]
	v_mfma_f32_16x16x32_bf16 v[46:49], v[170:173], v[204:207], v[46:49]
	v_mfma_f32_16x16x32_bf16 v[42:45], v[178:181], v[204:207], v[42:45]
	v_mfma_f32_16x16x32_bf16 v[38:41], v[170:173], v[212:215], v[38:41]
	v_mfma_f32_16x16x32_bf16 v[34:37], v[178:181], v[212:215], v[34:37]
	s_setprio 0
	s_barrier
	s_add_u32 s24, s25, 0x3c80180
	s_addc_u32 s25, s26, 0
	v_readfirstlane_b32 s23, v144
	s_mov_b32 m0, s23
	global_load_lds_dwordx4 v132, s[24:25]
	v_readfirstlane_b32 s23, v146
	s_mov_b32 m0, s23
	global_load_lds_dwordx4 v130, s[24:25]
	s_waitcnt vmcnt(6)
	s_barrier
	s_setprio 1
	v_mfma_f32_16x16x32_bf16 v[30:33], v[216:219], v[182:185], v[30:33]
	v_mfma_f32_16x16x32_bf16 v[26:29], v[224:227], v[182:185], v[26:29]
	v_mfma_f32_16x16x32_bf16 v[22:25], v[216:219], v[190:193], v[22:25]
	v_mfma_f32_16x16x32_bf16 v[18:21], v[224:227], v[190:193], v[18:21]
	v_mfma_f32_16x16x32_bf16 v[14:17], v[216:219], v[200:203], v[14:17]
	v_mfma_f32_16x16x32_bf16 v[10:13], v[224:227], v[200:203], v[10:13]
	v_mfma_f32_16x16x32_bf16 v[6:9], v[216:219], v[208:211], v[6:9]
	v_mfma_f32_16x16x32_bf16 v[2:5], v[224:227], v[208:211], v[2:5]
	v_mfma_f32_16x16x32_bf16 v[30:33], v[220:223], v[186:189], v[30:33]
	v_mfma_f32_16x16x32_bf16 v[26:29], v[228:231], v[186:189], v[26:29]
	v_mfma_f32_16x16x32_bf16 v[22:25], v[220:223], v[196:199], v[22:25]
	v_mfma_f32_16x16x32_bf16 v[18:21], v[228:231], v[196:199], v[18:21]
	v_mfma_f32_16x16x32_bf16 v[14:17], v[220:223], v[204:207], v[14:17]
	v_mfma_f32_16x16x32_bf16 v[10:13], v[228:231], v[204:207], v[10:13]
	v_mfma_f32_16x16x32_bf16 v[6:9], v[220:223], v[212:215], v[6:9]
	v_mfma_f32_16x16x32_bf16 v[2:5], v[228:231], v[212:215], v[2:5]
	s_setprio 0
	s_add_i32 s22, s22, 2
	s_add_u32 s4, s4, 0x100
	s_addc_u32 s5, s5, 0
	s_cmp_lt_u32 s22, 28
	s_barrier
	s_cbranch_scc1 .LBB0_562
	ds_read_b128 v[152:155], v149
	ds_read_b128 v[156:159], v149 offset:1024
	ds_read_b128 v[160:163], v149 offset:2048
	ds_read_b128 v[164:167], v149 offset:3072
	ds_read_b128 v[168:171], v141
	ds_read_b128 v[172:175], v141 offset:1024
	ds_read_b128 v[176:179], v139
	ds_read_b128 v[180:183], v139 offset:1024
	ds_read_b128 v[184:187], v137
	ds_read_b128 v[188:191], v137 offset:1024
	ds_read_b128 v[196:199], v135
	ds_read_b128 v[200:203], v135 offset:1024
	s_add_u32 s4, s19, 0x80f80
	s_addc_u32 s5, s21, 0
	v_lshl_add_u64 v[132:133], s[4:5], 0, v[132:133]
	v_readfirstlane_b32 s12, v148
	s_mov_b32 m0, s12
	global_load_lds_dwordx4 v[132:133], off
	v_lshl_add_u64 v[130:131], s[4:5], 0, v[130:131]
	v_readfirstlane_b32 s4, v150
	s_mov_b32 m0, s4
	global_load_lds_dwordx4 v[130:131], off
	s_barrier
	s_waitcnt lgkmcnt(0)
	s_setprio 1
	v_mfma_f32_16x16x32_bf16 v[126:129], v[152:155], v[168:171], v[126:129]
	v_mfma_f32_16x16x32_bf16 v[122:125], v[160:163], v[168:171], v[122:125]
	v_mfma_f32_16x16x32_bf16 v[114:117], v[160:163], v[176:179], v[114:117]
	v_mfma_f32_16x16x32_bf16 v[106:109], v[160:163], v[184:187], v[106:109]
	v_mfma_f32_16x16x32_bf16 v[98:101], v[160:163], v[196:199], v[98:101]
	v_mfma_f32_16x16x32_bf16 v[126:129], v[156:159], v[172:175], v[126:129]
	v_mfma_f32_16x16x32_bf16 v[122:125], v[164:167], v[172:175], v[122:125]
	v_mfma_f32_16x16x32_bf16 v[118:121], v[152:155], v[176:179], v[118:121]
	v_mfma_f32_16x16x32_bf16 v[114:117], v[164:167], v[180:183], v[114:117]
	v_mfma_f32_16x16x32_bf16 v[110:113], v[152:155], v[184:187], v[110:113]
	v_mfma_f32_16x16x32_bf16 v[106:109], v[164:167], v[188:191], v[106:109]
	v_mfma_f32_16x16x32_bf16 v[102:105], v[152:155], v[196:199], v[102:105]
	v_mfma_f32_16x16x32_bf16 v[98:101], v[164:167], v[200:203], v[98:101]
	v_mfma_f32_16x16x32_bf16 v[130:133], v[156:159], v[180:183], v[118:121]
	v_mfma_f32_16x16x32_bf16 v[148:151], v[156:159], v[188:191], v[110:113]
	v_mfma_f32_16x16x32_bf16 v[204:207], v[156:159], v[200:203], v[102:105]
	s_setprio 0
	s_barrier
	s_nop 0
	ds_read_b128 v[102:105], v147
	ds_read_b128 v[110:113], v147 offset:1024
	ds_read_b128 v[118:121], v147 offset:2048
	ds_read_b128 v[208:211], v147 offset:3072
	s_barrier
	s_waitcnt lgkmcnt(0)
	s_setprio 1
	v_mfma_f32_16x16x32_bf16 v[90:93], v[118:121], v[168:171], v[90:93]
	v_mfma_f32_16x16x32_bf16 v[82:85], v[118:121], v[176:179], v[82:85]
	v_mfma_f32_16x16x32_bf16 v[74:77], v[118:121], v[184:187], v[74:77]
	v_mfma_f32_16x16x32_bf16 v[66:69], v[118:121], v[196:199], v[66:69]
	v_mfma_f32_16x16x32_bf16 v[94:97], v[102:105], v[168:171], v[94:97]
	v_mfma_f32_16x16x32_bf16 v[90:93], v[208:211], v[172:175], v[90:93]
	v_mfma_f32_16x16x32_bf16 v[86:89], v[102:105], v[176:179], v[86:89]
	v_mfma_f32_16x16x32_bf16 v[82:85], v[208:211], v[180:183], v[82:85]
	v_mfma_f32_16x16x32_bf16 v[78:81], v[102:105], v[184:187], v[78:81]
	v_mfma_f32_16x16x32_bf16 v[74:77], v[208:211], v[188:191], v[74:77]
	v_mfma_f32_16x16x32_bf16 v[70:73], v[102:105], v[196:199], v[70:73]
	v_mfma_f32_16x16x32_bf16 v[66:69], v[208:211], v[200:203], v[66:69]
	v_mfma_f32_16x16x32_bf16 v[212:215], v[110:113], v[172:175], v[94:97]
	v_mfma_f32_16x16x32_bf16 v[168:171], v[110:113], v[180:183], v[86:89]
	v_mfma_f32_16x16x32_bf16 v[172:175], v[110:113], v[188:191], v[78:81]
	v_mfma_f32_16x16x32_bf16 v[176:179], v[110:113], v[200:203], v[70:73]
	s_setprio 0
	s_barrier
;   #define LDA(dst,b,h) for(int m=0;m<4;++m)for(int k=0;k<2;++k) \
;     dst[m][k]=*reinterpret_cast<const bf16x8*>((char*)SA(b,h)+lds_byte(wr*64+m*16+fr,k*32+fq*8))
;   #define LDB(dst,b,h) for(int n=0;n<2;++n)for(int k=0;k<2;++k) \
;     dst[n][k]=*reinterpret_cast<const bf16x8*>((char*)SB(b,h)+lds_byte(wc*32+n*16+fr,k*32+fq*8))
;   #define MMA(ai,bj,At,Bt_) do{__builtin_amdgcn_s_setprio(1); \
;     for(int m=0;m<4;++m)for(int n=0;n<2;++n)for(int k=0;k<2;++k) \
;       acc[ai][bj][m][n]=__builtin_amdgcn_mfma_f32_16x16x32_bf16(Bt_[n][k],At[m][k],acc[ai][bj][m][n],0,0,0); \
;     __builtin_amdgcn_s_setprio(0);}while(0)
;   #define WAIT_V(n) asm volatile("s_waitcnt vmcnt(" #n ")":::"memory")
;   #define WAIT_L(n) asm volatile("s_waitcnt lgkmcnt(" #n ")":::"memory")
;   #define BAR __builtin_amdgcn_s_barrier()
; template <bool TWO, class MID> ...
;     ...
;     LDA(At,0,1); WAIT_V(4); BAR; WAIT_L(0); MMA(1,0,At,B0); MMA(1,1,At,B1); BAR; }
;   { LDB(B0,1,0); LDA(At,1,0); WAIT_V(2); BAR; WAIT_L(0); MMA(0,0,At,B0); BAR;
	s_nop 0
	ds_read_b128 v[70:73], v141 offset:16384
	ds_read_b128 v[78:81], v141 offset:17408
	ds_read_b128 v[86:89], v139 offset:16384
	ds_read_b128 v[94:97], v139 offset:17408
	ds_read_b128 v[180:183], v137 offset:16384
	ds_read_b128 v[184:187], v137 offset:17408
	ds_read_b128 v[188:191], v135 offset:16384
	ds_read_b128 v[196:199], v135 offset:17408
	s_waitcnt vmcnt(4)
	s_barrier
	s_waitcnt lgkmcnt(0)
	s_setprio 1
	v_mfma_f32_16x16x32_bf16 v[62:65], v[152:155], v[70:73], v[62:65]
	v_mfma_f32_16x16x32_bf16 v[58:61], v[160:163], v[70:73], v[58:61]
	v_mfma_f32_16x16x32_bf16 v[54:57], v[152:155], v[86:89], v[54:57]
	v_mfma_f32_16x16x32_bf16 v[50:53], v[160:163], v[86:89], v[50:53]
	v_mfma_f32_16x16x32_bf16 v[38:41], v[152:155], v[188:191], v[38:41]
	v_mfma_f32_16x16x32_bf16 v[34:37], v[160:163], v[188:191], v[34:37]
	v_mfma_f32_16x16x32_bf16 v[62:65], v[156:159], v[78:81], v[62:65]
	v_mfma_f32_16x16x32_bf16 v[58:61], v[164:167], v[78:81], v[58:61]
	v_mfma_f32_16x16x32_bf16 v[54:57], v[156:159], v[94:97], v[54:57]
	v_mfma_f32_16x16x32_bf16 v[50:53], v[164:167], v[94:97], v[50:53]
	v_mfma_f32_16x16x32_bf16 v[46:49], v[152:155], v[180:183], v[46:49]
	v_mfma_f32_16x16x32_bf16 v[42:45], v[160:163], v[180:183], v[42:45]
	v_mfma_f32_16x16x32_bf16 v[38:41], v[156:159], v[196:199], v[38:41]
	v_mfma_f32_16x16x32_bf16 v[34:37], v[164:167], v[196:199], v[34:37]
	v_mfma_f32_16x16x32_bf16 v[200:203], v[156:159], v[184:187], v[46:49]
	v_mfma_f32_16x16x32_bf16 v[216:219], v[164:167], v[184:187], v[42:45]
	s_setprio 0
	s_setprio 1
	v_mfma_f32_16x16x32_bf16 v[22:25], v[102:105], v[86:89], v[22:25]
	v_mfma_f32_16x16x32_bf16 v[18:21], v[118:121], v[86:89], v[18:21]
	v_mfma_f32_16x16x32_bf16 v[6:9], v[102:105], v[188:191], v[6:9]
	v_mfma_f32_16x16x32_bf16 v[2:5], v[118:121], v[188:191], v[2:5]
	v_mfma_f32_16x16x32_bf16 v[30:33], v[102:105], v[70:73], v[30:33]
	v_mfma_f32_16x16x32_bf16 v[26:29], v[118:121], v[70:73], v[26:29]
	v_mfma_f32_16x16x32_bf16 v[22:25], v[110:113], v[94:97], v[22:25]
	v_mfma_f32_16x16x32_bf16 v[18:21], v[208:211], v[94:97], v[18:21]
	v_mfma_f32_16x16x32_bf16 v[14:17], v[102:105], v[180:183], v[14:17]
	v_mfma_f32_16x16x32_bf16 v[10:13], v[118:121], v[180:183], v[10:13]
	v_mfma_f32_16x16x32_bf16 v[6:9], v[110:113], v[196:199], v[6:9]
	v_mfma_f32_16x16x32_bf16 v[2:5], v[208:211], v[196:199], v[2:5]
	v_mfma_f32_16x16x32_bf16 v[152:155], v[110:113], v[78:81], v[30:33]
	v_mfma_f32_16x16x32_bf16 v[156:159], v[208:211], v[78:81], v[26:29]
	v_mfma_f32_16x16x32_bf16 v[160:163], v[110:113], v[184:187], v[14:17]
	v_mfma_f32_16x16x32_bf16 v[164:167], v[208:211], v[184:187], v[10:13]
	s_setprio 0
	s_barrier
	s_nop 0
	ds_read_b128 v[10:13], v145
	ds_read_b128 v[14:17], v145 offset:1024
	ds_read_b128 v[180:183], v145 offset:2048
	ds_read_b128 v[144:147], v145 offset:3072
	ds_read_b128 v[26:29], v141 offset:32768
	ds_read_b128 v[30:33], v141 offset:33792
	ds_read_b128 v[42:45], v139 offset:32768
	ds_read_b128 v[46:49], v139 offset:33792
	ds_read_b128 v[184:187], v137 offset:32768
	ds_read_b128 v[188:191], v137 offset:33792
	ds_read_b128 v[196:199], v135 offset:32768
	ds_read_b128 v[208:211], v135 offset:33792
	s_waitcnt vmcnt(2)
	s_barrier
	s_waitcnt lgkmcnt(0)
	s_setprio 1
	v_mfma_f32_16x16x32_bf16 v[70:73], v[10:13], v[26:29], v[126:129]
	v_mfma_f32_16x16x32_bf16 v[126:129], v[14:17], v[30:33], v[70:73]
	v_mfma_f32_16x16x32_bf16 v[70:73], v[180:183], v[26:29], v[122:125]
	v_mfma_f32_16x16x32_bf16 v[118:121], v[144:147], v[30:33], v[70:73]
	v_mfma_f32_16x16x32_bf16 v[70:73], v[10:13], v[42:45], v[130:133]
	v_mfma_f32_16x16x32_bf16 v[110:113], v[14:17], v[46:49], v[70:73]
	v_mfma_f32_16x16x32_bf16 v[70:73], v[180:183], v[42:45], v[114:117]
	v_mfma_f32_16x16x32_bf16 v[102:105], v[144:147], v[46:49], v[70:73]
	v_mfma_f32_16x16x32_bf16 v[70:73], v[10:13], v[184:187], v[148:151]
	v_mfma_f32_16x16x32_bf16 v[94:97], v[14:17], v[188:191], v[70:73]
	v_mfma_f32_16x16x32_bf16 v[70:73], v[180:183], v[184:187], v[106:109]
	v_mfma_f32_16x16x32_bf16 v[86:89], v[144:147], v[188:191], v[70:73]
	v_mfma_f32_16x16x32_bf16 v[70:73], v[10:13], v[196:199], v[204:207]
	v_mfma_f32_16x16x32_bf16 v[78:81], v[14:17], v[208:211], v[70:73]
	v_mfma_f32_16x16x32_bf16 v[70:73], v[180:183], v[196:199], v[98:101]
	v_mfma_f32_16x16x32_bf16 v[70:73], v[144:147], v[208:211], v[70:73]
	s_setprio 0
	s_barrier
;   #define LDA(dst,b,h) for(int m=0;m<4;++m)for(int k=0;k<2;++k) \
;     dst[m][k]=*reinterpret_cast<const bf16x8*>((char*)SA(b,h)+lds_byte(wr*64+m*16+fr,k*32+fq*8))
;   #define LDB(dst,b,h) for(int n=0;n<2;++n)for(int k=0;k<2;++k) \
;     dst[n][k]=*reinterpret_cast<const bf16x8*>((char*)SB(b,h)+lds_byte(wc*32+n*16+fr,k*32+fq*8))
;   #define MMA(ai,bj,At,Bt_) do{__builtin_amdgcn_s_setprio(1); \
;     for(int m=0;m<4;++m)for(int n=0;n<2;++n)for(int k=0;k<2;++k) \
;       acc[ai][bj][m][n]=__builtin_amdgcn_mfma_f32_16x16x32_bf16(Bt_[n][k],At[m][k],acc[ai][bj][m][n],0,0,0); \
;     __builtin_amdgcn_s_setprio(0);}while(0)
;   #define WAIT_V(n) asm volatile("s_waitcnt vmcnt(" #n ")":::"memory")
;   #define WAIT_L(n) asm volatile("s_waitcnt lgkmcnt(" #n ")":::"memory")
;   #define BAR __builtin_amdgcn_s_barrier()
; template <bool TWO, class MID> ...
;     ...
;     LDB(B1,1,1); WAIT_V(0); BAR; WAIT_L(0); MMA(0,1,At,B1); BAR;
;     LDA(At,1,1); BAR; WAIT_L(0); MMA(1,0,At,B0); MMA(1,1,At,B1); BAR; }
;   if(wr==0)BAR;
	ds_read_b128 v[130:133], v143
	ds_read_b128 v[148:151], v143 offset:1024
	ds_read_b128 v[204:207], v143 offset:2048
	ds_read_b128 v[220:223], v143 offset:3072
	s_waitcnt vmcnt(0)
	s_barrier
	s_waitcnt lgkmcnt(0)
	s_setprio 1
	v_mfma_f32_16x16x32_bf16 v[98:101], v[130:133], v[26:29], v[212:215]
	v_mfma_f32_16x16x32_bf16 v[26:29], v[204:207], v[26:29], v[90:93]
	v_mfma_f32_16x16x32_bf16 v[114:117], v[220:223], v[30:33], v[26:29]
	v_mfma_f32_16x16x32_bf16 v[26:29], v[130:133], v[42:45], v[168:171]
	v_mfma_f32_16x16x32_bf16 v[106:109], v[148:151], v[46:49], v[26:29]
	v_mfma_f32_16x16x32_bf16 v[26:29], v[204:207], v[42:45], v[82:85]
	v_mfma_f32_16x16x32_bf16 v[122:125], v[148:151], v[30:33], v[98:101]
	v_mfma_f32_16x16x32_bf16 v[98:101], v[220:223], v[46:49], v[26:29]
	v_mfma_f32_16x16x32_bf16 v[26:29], v[130:133], v[184:187], v[172:175]
	v_mfma_f32_16x16x32_bf16 v[90:93], v[148:151], v[188:191], v[26:29]
	v_mfma_f32_16x16x32_bf16 v[26:29], v[204:207], v[184:187], v[74:77]
	v_mfma_f32_16x16x32_bf16 v[82:85], v[220:223], v[188:191], v[26:29]
	v_mfma_f32_16x16x32_bf16 v[26:29], v[130:133], v[196:199], v[176:179]
	v_mfma_f32_16x16x32_bf16 v[74:77], v[148:151], v[208:211], v[26:29]
	v_mfma_f32_16x16x32_bf16 v[26:29], v[204:207], v[196:199], v[66:69]
	v_mfma_f32_16x16x32_bf16 v[66:69], v[220:223], v[208:211], v[26:29]
	s_setprio 0
	s_barrier
	ds_read_b128 v[168:171], v141 offset:49152
	ds_read_b128 v[140:143], v141 offset:50176
	ds_read_b128 v[172:175], v139 offset:49152
	ds_read_b128 v[176:179], v139 offset:50176
	ds_read_b128 v[184:187], v137 offset:49152
	ds_read_b128 v[136:139], v137 offset:50176
	ds_read_b128 v[188:191], v135 offset:49152
	ds_read_b128 v[196:199], v135 offset:50176
	s_barrier
	s_waitcnt lgkmcnt(0)
	s_setprio 1
	v_mfma_f32_16x16x32_bf16 v[26:29], v[10:13], v[168:171], v[62:65]
	v_mfma_f32_16x16x32_bf16 v[62:65], v[14:17], v[140:143], v[26:29]
	v_mfma_f32_16x16x32_bf16 v[26:29], v[180:183], v[168:171], v[58:61]
	v_mfma_f32_16x16x32_bf16 v[58:61], v[144:147], v[140:143], v[26:29]
	v_mfma_f32_16x16x32_bf16 v[26:29], v[10:13], v[172:175], v[54:57]
	v_mfma_f32_16x16x32_bf16 v[46:49], v[14:17], v[176:179], v[26:29]
	v_mfma_f32_16x16x32_bf16 v[26:29], v[180:183], v[172:175], v[50:53]
	v_mfma_f32_16x16x32_bf16 v[42:45], v[144:147], v[176:179], v[26:29]
	v_mfma_f32_16x16x32_bf16 v[26:29], v[10:13], v[184:187], v[200:203]
	v_mfma_f32_16x16x32_bf16 v[10:13], v[10:13], v[188:191], v[38:41]
	v_mfma_f32_16x16x32_bf16 v[30:33], v[14:17], v[136:139], v[26:29]
	v_mfma_f32_16x16x32_bf16 v[26:29], v[180:183], v[184:187], v[216:219]
	v_mfma_f32_16x16x32_bf16 v[14:17], v[14:17], v[196:199], v[10:13]
	v_mfma_f32_16x16x32_bf16 v[10:13], v[180:183], v[188:191], v[34:37]
	v_mfma_f32_16x16x32_bf16 v[26:29], v[144:147], v[136:139], v[26:29]
	v_mfma_f32_16x16x32_bf16 v[10:13], v[144:147], v[196:199], v[10:13]
	s_setprio 0
	s_setprio 1
	v_mfma_f32_16x16x32_bf16 v[34:37], v[130:133], v[168:171], v[152:155]
	v_mfma_f32_16x16x32_bf16 v[54:57], v[148:151], v[140:143], v[34:37]
	v_mfma_f32_16x16x32_bf16 v[34:37], v[204:207], v[168:171], v[156:159]
	v_mfma_f32_16x16x32_bf16 v[18:21], v[204:207], v[172:175], v[18:21]
	v_mfma_f32_16x16x32_bf16 v[50:53], v[220:223], v[140:143], v[34:37]
	v_mfma_f32_16x16x32_bf16 v[22:25], v[130:133], v[172:175], v[22:25]
	v_mfma_f32_16x16x32_bf16 v[34:37], v[220:223], v[176:179], v[18:21]
	v_mfma_f32_16x16x32_bf16 v[18:21], v[130:133], v[184:187], v[160:163]
	v_mfma_f32_16x16x32_bf16 v[38:41], v[148:151], v[176:179], v[22:25]
	v_mfma_f32_16x16x32_bf16 v[22:25], v[148:151], v[136:139], v[18:21]
	v_mfma_f32_16x16x32_bf16 v[18:21], v[204:207], v[184:187], v[164:167]
	v_mfma_f32_16x16x32_bf16 v[6:9], v[130:133], v[188:191], v[6:9]
	v_mfma_f32_16x16x32_bf16 v[2:5], v[204:207], v[188:191], v[2:5]
	v_mfma_f32_16x16x32_bf16 v[18:21], v[220:223], v[136:139], v[18:21]
	v_mfma_f32_16x16x32_bf16 v[6:9], v[148:151], v[196:199], v[6:9]
	v_mfma_f32_16x16x32_bf16 v[2:5], v[220:223], v[196:199], v[2:5]
	s_setprio 0
	v_cmp_gt_u32_e32 vcc, s30, v1
	s_barrier
	s_and_saveexec_b64 s[4:5], vcc
	s_cbranch_execz .LBB0_565
	s_barrier

;   #define LDA(dst,b,h) for(int m=0;m<4;++m)for(int k=0;k<2;++k) \
;     dst[m][k]=*reinterpret_cast<const bf16x8*>((char*)SA(b,h)+lds_byte(wr*64+m*16+fr,k*32+fq*8))
;   #define LDB(dst,b,h) for(int n=0;n<2;++n)for(int k=0;k<2;++k) \
;     dst[n][k]=*reinterpret_cast<const bf16x8*>((char*)SB(b,h)+lds_byte(wc*32+n*16+fr,k*32+fq*8))
;   #define MMA(ai,bj,At,Bt_) do{__builtin_amdgcn_s_setprio(1); \
;     for(int m=0;m<4;++m)for(int n=0;n<2;++n)for(int k=0;k<2;++k) \
;       acc[ai][bj][m][n]=__builtin_amdgcn_mfma_f32_16x16x32_bf16(Bt_[n][k],At[m][k],acc[ai][bj][m][n],0,0,0); \
;     __builtin_amdgcn_s_setprio(0);}while(0)
;   #define WAIT_V(n) asm volatile("s_waitcnt vmcnt(" #n ")":::"memory")
;   #define WAIT_L(n) asm volatile("s_waitcnt lgkmcnt(" #n ")":::"memory")
;   #define BAR __builtin_amdgcn_s_barrier()
;   #define SCHED __builtin_amdgcn_sched_barrier(0)
; __device__ __forceinline__ void gll16(const void* g, const void* l) {
;   const unsigned m = __builtin_amdgcn_readfirstlane((unsigned)(uintptr_t)l);
;   asm volatile("s_mov_b32 m0, %0\n\tglobal_load_lds_dwordx4 %1, off" :: "s"(m), "v"(g) : "memory");
; template <bool TWO, class MID> ...
;     ...
;     LDB(B0,0,0); SCHED; LDA(At,0,0); STAGE_A(SA(1,1),1,t+1);
;     WAIT_L(8); BAR; WAIT_L(0); MMA(0,0,At,B0); BAR; SCHED;
;     LDB(B1,0,1); STAGE_B(SB(0,0),0,t+2);
;     BAR; WAIT_L(0); MMA(0,1,At,B1); BAR;
;     LDA(At,0,1); STAGE_A(SA(0,0),0,t+2);
;     BAR; WAIT_L(0); MMA(1,0,At,B0); BAR; SCHED;
;     STAGE_B(SB(0,1),1,t+2);
;     WAIT_V(6); BAR; MMA(1,1,At,B1); BAR;
;     LDB(B0,1,0); SCHED; LDA(At,1,0); STAGE_A(SA(0,1),1,t+2);
;     WAIT_L(8); BAR; WAIT_L(0); MMA(0,0,At,B0); BAR; SCHED;
;     LDB(B1,1,1); STAGE_B(SB(1,0),0,t+3);
;     BAR; WAIT_L(0); MMA(0,1,At,B1); BAR;
;     LDA(At,1,1); STAGE_A(SA(1,0),0,t+3);
;     BAR; WAIT_L(0); MMA(1,0,At,B0); BAR; SCHED;
;     STAGE_B(SB(1,1),1,t+3);
;     WAIT_V(6); BAR; MMA(1,1,At,B1); BAR;
.LBB0_620:
	ds_read_b128 v[166:169], v149
	ds_read_b128 v[170:173], v149 offset:1024
	ds_read_b128 v[174:177], v149 offset:2048
	ds_read_b128 v[178:181], v149 offset:3072
	ds_read_b128 v[182:185], v141
	ds_read_b128 v[186:189], v141 offset:1024
	ds_read_b128 v[190:193], v139
	ds_read_b128 v[196:199], v139 offset:1024
	ds_read_b128 v[200:203], v137
	ds_read_b128 v[204:207], v137 offset:1024
	ds_read_b128 v[208:211], v135
	ds_read_b128 v[212:215], v135 offset:1024
	s_add_u32 s15, s0, s16
	s_addc_u32 s18, s1, s17
	s_add_u32 s24, s15, 0x10200080
	s_addc_u32 s25, s18, 0
	v_readfirstlane_b32 s19, v148
	s_mov_b32 m0, s19
	global_load_lds_dwordx4 v132, s[24:25]
	v_readfirstlane_b32 s19, v150
	s_mov_b32 m0, s19
	global_load_lds_dwordx4 v130, s[24:25]
	s_waitcnt lgkmcnt(8)
	s_barrier
	s_waitcnt lgkmcnt(0)
	s_setprio 1
	v_mfma_f32_16x16x32_bf16 v[126:129], v[166:169], v[182:185], v[126:129]
	v_mfma_f32_16x16x32_bf16 v[122:125], v[174:177], v[182:185], v[122:125]
	v_mfma_f32_16x16x32_bf16 v[118:121], v[166:169], v[190:193], v[118:121]
	v_mfma_f32_16x16x32_bf16 v[114:117], v[174:177], v[190:193], v[114:117]
	v_mfma_f32_16x16x32_bf16 v[110:113], v[166:169], v[200:203], v[110:113]
	v_mfma_f32_16x16x32_bf16 v[106:109], v[174:177], v[200:203], v[106:109]
	v_mfma_f32_16x16x32_bf16 v[102:105], v[166:169], v[208:211], v[102:105]
	v_mfma_f32_16x16x32_bf16 v[98:101], v[174:177], v[208:211], v[98:101]
	v_mfma_f32_16x16x32_bf16 v[126:129], v[170:173], v[186:189], v[126:129]
	v_mfma_f32_16x16x32_bf16 v[122:125], v[178:181], v[186:189], v[122:125]
	v_mfma_f32_16x16x32_bf16 v[118:121], v[170:173], v[196:199], v[118:121]
	v_mfma_f32_16x16x32_bf16 v[114:117], v[178:181], v[196:199], v[114:117]
	v_mfma_f32_16x16x32_bf16 v[110:113], v[170:173], v[204:207], v[110:113]
	v_mfma_f32_16x16x32_bf16 v[106:109], v[178:181], v[204:207], v[106:109]
	v_mfma_f32_16x16x32_bf16 v[102:105], v[170:173], v[212:215], v[102:105]
	v_mfma_f32_16x16x32_bf16 v[98:101], v[178:181], v[212:215], v[98:101]
	s_setprio 0
	s_barrier
	s_add_u32 s19, s0, s4
	ds_read_b128 v[216:219], v147
	ds_read_b128 v[220:223], v147 offset:1024
	ds_read_b128 v[224:227], v147 offset:2048
	ds_read_b128 v[228:231], v147 offset:3072
	s_addc_u32 s24, s1, s5
	s_add_u32 s26, s19, 0x5c00100
	s_addc_u32 s27, s24, 0
	v_readfirstlane_b32 s25, v152
	s_mov_b32 m0, s25
	global_load_lds_dwordx4 v132, s[26:27]
	v_readfirstlane_b32 s25, v154
	s_mov_b32 m0, s25
	global_load_lds_dwordx4 v130, s[26:27]
	s_barrier
	s_waitcnt lgkmcnt(0)
	s_setprio 1
	v_mfma_f32_16x16x32_bf16 v[94:97], v[216:219], v[182:185], v[94:97]
	v_mfma_f32_16x16x32_bf16 v[90:93], v[224:227], v[182:185], v[90:93]
	v_mfma_f32_16x16x32_bf16 v[86:89], v[216:219], v[190:193], v[86:89]
	v_mfma_f32_16x16x32_bf16 v[82:85], v[224:227], v[190:193], v[82:85]
	v_mfma_f32_16x16x32_bf16 v[78:81], v[216:219], v[200:203], v[78:81]
	v_mfma_f32_16x16x32_bf16 v[74:77], v[224:227], v[200:203], v[74:77]
	v_mfma_f32_16x16x32_bf16 v[70:73], v[216:219], v[208:211], v[70:73]
	v_mfma_f32_16x16x32_bf16 v[66:69], v[224:227], v[208:211], v[66:69]
	v_mfma_f32_16x16x32_bf16 v[94:97], v[220:223], v[186:189], v[94:97]
	v_mfma_f32_16x16x32_bf16 v[90:93], v[228:231], v[186:189], v[90:93]
	v_mfma_f32_16x16x32_bf16 v[86:89], v[220:223], v[196:199], v[86:89]
	v_mfma_f32_16x16x32_bf16 v[82:85], v[228:231], v[196:199], v[82:85]
	v_mfma_f32_16x16x32_bf16 v[78:81], v[220:223], v[204:207], v[78:81]
	v_mfma_f32_16x16x32_bf16 v[74:77], v[228:231], v[204:207], v[74:77]
	v_mfma_f32_16x16x32_bf16 v[70:73], v[220:223], v[212:215], v[70:73]
	v_mfma_f32_16x16x32_bf16 v[66:69], v[228:231], v[212:215], v[66:69]
	s_setprio 0
	s_barrier
	ds_read_b128 v[182:185], v141 offset:16384
	ds_read_b128 v[186:189], v141 offset:17408
	ds_read_b128 v[190:193], v139 offset:16384
	ds_read_b128 v[196:199], v139 offset:17408
	ds_read_b128 v[200:203], v137 offset:16384
	ds_read_b128 v[204:207], v137 offset:17408
	ds_read_b128 v[208:211], v135 offset:16384
	ds_read_b128 v[212:215], v135 offset:17408
	s_add_u32 s26, s15, 0x10000100
	s_addc_u32 s27, s18, 0
	v_readfirstlane_b32 s25, v138
	s_mov_b32 m0, s25
	global_load_lds_dwordx4 v132, s[26:27]
	v_readfirstlane_b32 s25, v156
	s_mov_b32 m0, s25
	global_load_lds_dwordx4 v130, s[26:27]
	s_barrier
	s_waitcnt lgkmcnt(0)
	s_setprio 1
	v_mfma_f32_16x16x32_bf16 v[62:65], v[166:169], v[182:185], v[62:65]
	v_mfma_f32_16x16x32_bf16 v[58:61], v[174:177], v[182:185], v[58:61]
	v_mfma_f32_16x16x32_bf16 v[54:57], v[166:169], v[190:193], v[54:57]
	v_mfma_f32_16x16x32_bf16 v[50:53], v[174:177], v[190:193], v[50:53]
	v_mfma_f32_16x16x32_bf16 v[46:49], v[166:169], v[200:203], v[46:49]
	v_mfma_f32_16x16x32_bf16 v[42:45], v[174:177], v[200:203], v[42:45]
	v_mfma_f32_16x16x32_bf16 v[38:41], v[166:169], v[208:211], v[38:41]
	v_mfma_f32_16x16x32_bf16 v[34:37], v[174:177], v[208:211], v[34:37]
	v_mfma_f32_16x16x32_bf16 v[62:65], v[170:173], v[186:189], v[62:65]
	v_mfma_f32_16x16x32_bf16 v[58:61], v[178:181], v[186:189], v[58:61]
	v_mfma_f32_16x16x32_bf16 v[54:57], v[170:173], v[196:199], v[54:57]
	v_mfma_f32_16x16x32_bf16 v[50:53], v[178:181], v[196:199], v[50:53]
	v_mfma_f32_16x16x32_bf16 v[46:49], v[170:173], v[204:207], v[46:49]
	v_mfma_f32_16x16x32_bf16 v[42:45], v[178:181], v[204:207], v[42:45]
	v_mfma_f32_16x16x32_bf16 v[38:41], v[170:173], v[212:215], v[38:41]
	v_mfma_f32_16x16x32_bf16 v[34:37], v[178:181], v[212:215], v[34:37]
	s_setprio 0
	s_barrier
	s_add_u32 s26, s19, 0x5e00100
	s_addc_u32 s27, s24, 0
	v_readfirstlane_b32 s25, v158
	s_mov_b32 m0, s25
	global_load_lds_dwordx4 v132, s[26:27]
	v_readfirstlane_b32 s25, v160
	s_mov_b32 m0, s25
	global_load_lds_dwordx4 v130, s[26:27]
	s_waitcnt vmcnt(6)
	s_barrier
;   #define LDA(dst,b,h) for(int m=0;m<4;++m)for(int k=0;k<2;++k) \
;     dst[m][k]=*reinterpret_cast<const bf16x8*>((char*)SA(b,h)+lds_byte(wr*64+m*16+fr,k*32+fq*8))
;   #define LDB(dst,b,h) for(int n=0;n<2;++n)for(int k=0;k<2;++k) \
;     dst[n][k]=*reinterpret_cast<const bf16x8*>((char*)SB(b,h)+lds_byte(wc*32+n*16+fr,k*32+fq*8))
;   #define MMA(ai,bj,At,Bt_) do{__builtin_amdgcn_s_setprio(1); \
;     for(int m=0;m<4;++m)for(int n=0;n<2;++n)for(int k=0;k<2;++k) \
;       acc[ai][bj][m][n]=__builtin_amdgcn_mfma_f32_16x16x32_bf16(Bt_[n][k],At[m][k],acc[ai][bj][m][n],0,0,0); \
;     __builtin_amdgcn_s_setprio(0);}while(0)
;   #define WAIT_V(n) asm volatile("s_waitcnt vmcnt(" #n ")":::"memory")
;   #define WAIT_L(n) asm volatile("s_waitcnt lgkmcnt(" #n ")":::"memory")
;   #define BAR __builtin_amdgcn_s_barrier()
;   #define SCHED __builtin_amdgcn_sched_barrier(0)
; template <bool TWO, class MID> ...
;     ...
;     LDA(At,0,1); STAGE_A(SA(0,0),0,t+2);
;     BAR; WAIT_L(0); MMA(1,0,At,B0); BAR; SCHED;
;     STAGE_B(SB(0,1),1,t+2);
;     WAIT_V(6); BAR; MMA(1,1,At,B1); BAR;
;     LDB(B0,1,0); SCHED; LDA(At,1,0); STAGE_A(SA(0,1),1,t+2);
;     WAIT_L(8); BAR; WAIT_L(0); MMA(0,0,At,B0); BAR; SCHED;
;     LDB(B1,1,1); STAGE_B(SB(1,0),0,t+3);
;     BAR; WAIT_L(0); MMA(0,1,At,B1); BAR;
;     LDA(At,1,1); STAGE_A(SA(1,0),0,t+3);
;     BAR; WAIT_L(0); MMA(1,0,At,B0); BAR; SCHED;
	s_setprio 1
	v_mfma_f32_16x16x32_bf16 v[30:33], v[216:219], v[182:185], v[30:33]
	v_mfma_f32_16x16x32_bf16 v[26:29], v[224:227], v[182:185], v[26:29]
	v_mfma_f32_16x16x32_bf16 v[22:25], v[216:219], v[190:193], v[22:25]
	v_mfma_f32_16x16x32_bf16 v[18:21], v[224:227], v[190:193], v[18:21]
	v_mfma_f32_16x16x32_bf16 v[14:17], v[216:219], v[200:203], v[14:17]
	v_mfma_f32_16x16x32_bf16 v[10:13], v[224:227], v[200:203], v[10:13]
	v_mfma_f32_16x16x32_bf16 v[6:9], v[216:219], v[208:211], v[6:9]
	v_mfma_f32_16x16x32_bf16 v[2:5], v[224:227], v[208:211], v[2:5]
	v_mfma_f32_16x16x32_bf16 v[30:33], v[220:223], v[186:189], v[30:33]
	v_mfma_f32_16x16x32_bf16 v[26:29], v[228:231], v[186:189], v[26:29]
	v_mfma_f32_16x16x32_bf16 v[22:25], v[220:223], v[196:199], v[22:25]
	v_mfma_f32_16x16x32_bf16 v[18:21], v[228:231], v[196:199], v[18:21]
	v_mfma_f32_16x16x32_bf16 v[14:17], v[220:223], v[204:207], v[14:17]
	v_mfma_f32_16x16x32_bf16 v[10:13], v[228:231], v[204:207], v[10:13]
	v_mfma_f32_16x16x32_bf16 v[6:9], v[220:223], v[212:215], v[6:9]
	v_mfma_f32_16x16x32_bf16 v[2:5], v[228:231], v[212:215], v[2:5]
	s_setprio 0
	s_barrier
	ds_read_b128 v[166:169], v145
	ds_read_b128 v[170:173], v145 offset:1024
	ds_read_b128 v[174:177], v145 offset:2048
	ds_read_b128 v[178:181], v145 offset:3072
	ds_read_b128 v[182:185], v141 offset:32768
	ds_read_b128 v[186:189], v141 offset:33792
	ds_read_b128 v[190:193], v139 offset:32768
	ds_read_b128 v[196:199], v139 offset:33792
	ds_read_b128 v[200:203], v137 offset:32768
	ds_read_b128 v[204:207], v137 offset:33792
	ds_read_b128 v[208:211], v135 offset:32768
	ds_read_b128 v[212:215], v135 offset:33792
	s_add_u32 s26, s15, 0x10200100
	s_addc_u32 s27, s18, 0
	v_readfirstlane_b32 s25, v162
	s_mov_b32 m0, s25
	global_load_lds_dwordx4 v132, s[26:27]
	v_readfirstlane_b32 s25, v164
	s_mov_b32 m0, s25
	global_load_lds_dwordx4 v130, s[26:27]
	s_waitcnt lgkmcnt(8)
	s_barrier
	s_waitcnt lgkmcnt(0)
	s_setprio 1
	v_mfma_f32_16x16x32_bf16 v[126:129], v[166:169], v[182:185], v[126:129]
	v_mfma_f32_16x16x32_bf16 v[122:125], v[174:177], v[182:185], v[122:125]
	v_mfma_f32_16x16x32_bf16 v[118:121], v[166:169], v[190:193], v[118:121]
	v_mfma_f32_16x16x32_bf16 v[114:117], v[174:177], v[190:193], v[114:117]
	v_mfma_f32_16x16x32_bf16 v[110:113], v[166:169], v[200:203], v[110:113]
	v_mfma_f32_16x16x32_bf16 v[106:109], v[174:177], v[200:203], v[106:109]
	v_mfma_f32_16x16x32_bf16 v[102:105], v[166:169], v[208:211], v[102:105]
	v_mfma_f32_16x16x32_bf16 v[98:101], v[174:177], v[208:211], v[98:101]
	v_mfma_f32_16x16x32_bf16 v[126:129], v[170:173], v[186:189], v[126:129]
	v_mfma_f32_16x16x32_bf16 v[122:125], v[178:181], v[186:189], v[122:125]
	v_mfma_f32_16x16x32_bf16 v[118:121], v[170:173], v[196:199], v[118:121]
	v_mfma_f32_16x16x32_bf16 v[114:117], v[178:181], v[196:199], v[114:117]
	v_mfma_f32_16x16x32_bf16 v[110:113], v[170:173], v[204:207], v[110:113]
	v_mfma_f32_16x16x32_bf16 v[106:109], v[178:181], v[204:207], v[106:109]
	v_mfma_f32_16x16x32_bf16 v[102:105], v[170:173], v[212:215], v[102:105]
	v_mfma_f32_16x16x32_bf16 v[98:101], v[178:181], v[212:215], v[98:101]
	s_setprio 0
	s_barrier
	ds_read_b128 v[216:219], v143
	ds_read_b128 v[220:223], v143 offset:1024
	ds_read_b128 v[224:227], v143 offset:2048
	ds_read_b128 v[228:231], v143 offset:3072
	s_add_u32 s26, s19, 0x5c00180
	s_addc_u32 s27, s24, 0
	v_readfirstlane_b32 s25, v134
	s_mov_b32 m0, s25
	global_load_lds_dwordx4 v132, s[26:27]
	v_readfirstlane_b32 s25, v136
	s_mov_b32 m0, s25
	global_load_lds_dwordx4 v130, s[26:27]
	s_barrier
	s_waitcnt lgkmcnt(0)
	s_setprio 1
	v_mfma_f32_16x16x32_bf16 v[94:97], v[216:219], v[182:185], v[94:97]
	v_mfma_f32_16x16x32_bf16 v[90:93], v[224:227], v[182:185], v[90:93]
	v_mfma_f32_16x16x32_bf16 v[86:89], v[216:219], v[190:193], v[86:89]
	v_mfma_f32_16x16x32_bf16 v[82:85], v[224:227], v[190:193], v[82:85]
	v_mfma_f32_16x16x32_bf16 v[78:81], v[216:219], v[200:203], v[78:81]
	v_mfma_f32_16x16x32_bf16 v[74:77], v[224:227], v[200:203], v[74:77]
	v_mfma_f32_16x16x32_bf16 v[70:73], v[216:219], v[208:211], v[70:73]
	v_mfma_f32_16x16x32_bf16 v[66:69], v[224:227], v[208:211], v[66:69]
	v_mfma_f32_16x16x32_bf16 v[94:97], v[220:223], v[186:189], v[94:97]
	v_mfma_f32_16x16x32_bf16 v[90:93], v[228:231], v[186:189], v[90:93]
	v_mfma_f32_16x16x32_bf16 v[86:89], v[220:223], v[196:199], v[86:89]
	v_mfma_f32_16x16x32_bf16 v[82:85], v[228:231], v[196:199], v[82:85]
	v_mfma_f32_16x16x32_bf16 v[78:81], v[220:223], v[204:207], v[78:81]
	v_mfma_f32_16x16x32_bf16 v[74:77], v[228:231], v[204:207], v[74:77]
	v_mfma_f32_16x16x32_bf16 v[70:73], v[220:223], v[212:215], v[70:73]
	v_mfma_f32_16x16x32_bf16 v[66:69], v[228:231], v[212:215], v[66:69]
	s_setprio 0
	s_barrier
	ds_read_b128 v[182:185], v141 offset:49152
	ds_read_b128 v[186:189], v141 offset:50176
	ds_read_b128 v[190:193], v139 offset:49152
	ds_read_b128 v[196:199], v139 offset:50176
	ds_read_b128 v[200:203], v137 offset:49152
	ds_read_b128 v[204:207], v137 offset:50176
	ds_read_b128 v[208:211], v135 offset:49152
	ds_read_b128 v[212:215], v135 offset:50176
	s_add_u32 s26, s15, 0x10000180
	s_addc_u32 s27, s18, 0
	v_readfirstlane_b32 s15, v140
	s_mov_b32 m0, s15
	global_load_lds_dwordx4 v132, s[26:27]
	v_readfirstlane_b32 s15, v142
	s_mov_b32 m0, s15
	global_load_lds_dwordx4 v130, s[26:27]
	s_barrier
;   #define LDA(dst,b,h) for(int m=0;m<4;++m)for(int k=0;k<2;++k) \
;     dst[m][k]=*reinterpret_cast<const bf16x8*>((char*)SA(b,h)+lds_byte(wr*64+m*16+fr,k*32+fq*8))
;   #define LDB(dst,b,h) for(int n=0;n<2;++n)for(int k=0;k<2;++k) \
;     dst[n][k]=*reinterpret_cast<const bf16x8*>((char*)SB(b,h)+lds_byte(wc*32+n*16+fr,k*32+fq*8))
;   #define MMA(ai,bj,At,Bt_) do{__builtin_amdgcn_s_setprio(1); \
;     for(int m=0;m<4;++m)for(int n=0;n<2;++n)for(int k=0;k<2;++k) \
;       acc[ai][bj][m][n]=__builtin_amdgcn_mfma_f32_16x16x32_bf16(Bt_[n][k],At[m][k],acc[ai][bj][m][n],0,0,0); \
;     __builtin_amdgcn_s_setprio(0);}while(0)
;   #define WAIT_V(n) asm volatile("s_waitcnt vmcnt(" #n ")":::"memory")
;   #define WAIT_L(n) asm volatile("s_waitcnt lgkmcnt(" #n ")":::"memory")
;   #define BAR __builtin_amdgcn_s_barrier()
;   #define SCHED __builtin_amdgcn_sched_barrier(0)
; template <bool TWO, class MID> ...
;     ...
;     LDB(B1,1,1); STAGE_B(SB(1,0),0,t+3);
;     BAR; WAIT_L(0); MMA(0,1,At,B1); BAR;
;     LDA(At,1,1); STAGE_A(SA(1,0),0,t+3);
;     BAR; WAIT_L(0); MMA(1,0,At,B0); BAR; SCHED;
;     STAGE_B(SB(1,1),1,t+3);
;     WAIT_V(6); BAR; MMA(1,1,At,B1); BAR;
;   }
;   { LDB(B0,0,0); LDA(At,0,0); STAGE_A(SA(1,1),1,nt-1);
;     BAR; WAIT_L(0); MMA(0,0,At,B0); BAR;
;     LDB(B1,0,1); BAR; WAIT_L(0); MMA(0,1,At,B1); BAR;
;     LDA(At,0,1); WAIT_V(4); BAR; WAIT_L(0); MMA(1,0,At,B0); MMA(1,1,At,B1); BAR; }
	s_waitcnt lgkmcnt(0)
	s_setprio 1
	v_mfma_f32_16x16x32_bf16 v[62:65], v[166:169], v[182:185], v[62:65]
	v_mfma_f32_16x16x32_bf16 v[58:61], v[174:177], v[182:185], v[58:61]
	v_mfma_f32_16x16x32_bf16 v[54:57], v[166:169], v[190:193], v[54:57]
	v_mfma_f32_16x16x32_bf16 v[50:53], v[174:177], v[190:193], v[50:53]
	v_mfma_f32_16x16x32_bf16 v[46:49], v[166:169], v[200:203], v[46:49]
	v_mfma_f32_16x16x32_bf16 v[42:45], v[174:177], v[200:203], v[42:45]
	v_mfma_f32_16x16x32_bf16 v[38:41], v[166:169], v[208:211], v[38:41]
	v_mfma_f32_16x16x32_bf16 v[34:37], v[174:177], v[208:211], v[34:37]
	v_mfma_f32_16x16x32_bf16 v[62:65], v[170:173], v[186:189], v[62:65]
	v_mfma_f32_16x16x32_bf16 v[58:61], v[178:181], v[186:189], v[58:61]
	v_mfma_f32_16x16x32_bf16 v[54:57], v[170:173], v[196:199], v[54:57]
	v_mfma_f32_16x16x32_bf16 v[50:53], v[178:181], v[196:199], v[50:53]
	v_mfma_f32_16x16x32_bf16 v[46:49], v[170:173], v[204:207], v[46:49]
	v_mfma_f32_16x16x32_bf16 v[42:45], v[178:181], v[204:207], v[42:45]
	v_mfma_f32_16x16x32_bf16 v[38:41], v[170:173], v[212:215], v[38:41]
	v_mfma_f32_16x16x32_bf16 v[34:37], v[178:181], v[212:215], v[34:37]
	s_setprio 0
	s_barrier
	s_add_u32 s18, s19, 0x5e00180
	s_addc_u32 s19, s24, 0
	v_readfirstlane_b32 s15, v144
	s_mov_b32 m0, s15
	global_load_lds_dwordx4 v132, s[18:19]
	v_readfirstlane_b32 s15, v146
	s_mov_b32 m0, s15
	global_load_lds_dwordx4 v130, s[18:19]
	s_waitcnt vmcnt(6)
	s_barrier
	s_setprio 1
	v_mfma_f32_16x16x32_bf16 v[30:33], v[216:219], v[182:185], v[30:33]
	v_mfma_f32_16x16x32_bf16 v[26:29], v[224:227], v[182:185], v[26:29]
	v_mfma_f32_16x16x32_bf16 v[22:25], v[216:219], v[190:193], v[22:25]
	v_mfma_f32_16x16x32_bf16 v[18:21], v[224:227], v[190:193], v[18:21]
	v_mfma_f32_16x16x32_bf16 v[14:17], v[216:219], v[200:203], v[14:17]
	v_mfma_f32_16x16x32_bf16 v[10:13], v[224:227], v[200:203], v[10:13]
	v_mfma_f32_16x16x32_bf16 v[6:9], v[216:219], v[208:211], v[6:9]
	v_mfma_f32_16x16x32_bf16 v[2:5], v[224:227], v[208:211], v[2:5]
	v_mfma_f32_16x16x32_bf16 v[30:33], v[220:223], v[186:189], v[30:33]
	v_mfma_f32_16x16x32_bf16 v[26:29], v[228:231], v[186:189], v[26:29]
	v_mfma_f32_16x16x32_bf16 v[22:25], v[220:223], v[196:199], v[22:25]
	v_mfma_f32_16x16x32_bf16 v[18:21], v[228:231], v[196:199], v[18:21]
	v_mfma_f32_16x16x32_bf16 v[14:17], v[220:223], v[204:207], v[14:17]
	v_mfma_f32_16x16x32_bf16 v[10:13], v[228:231], v[204:207], v[10:13]
	v_mfma_f32_16x16x32_bf16 v[6:9], v[220:223], v[212:215], v[6:9]
	v_mfma_f32_16x16x32_bf16 v[2:5], v[228:231], v[212:215], v[2:5]
	s_setprio 0
	s_add_i32 s14, s14, 2
	s_add_u32 s0, s0, 0x100
	s_addc_u32 s1, s1, 0
	s_cmpk_lt_u32 s14, 0x7c
	s_barrier
	s_cbranch_scc1 .LBB0_620
	ds_read_b128 v[152:155], v149
	ds_read_b128 v[156:159], v149 offset:1024
	ds_read_b128 v[160:163], v149 offset:2048
	ds_read_b128 v[164:167], v149 offset:3072
	ds_read_b128 v[168:171], v141
	ds_read_b128 v[172:175], v141 offset:1024
	ds_read_b128 v[176:179], v139
	ds_read_b128 v[180:183], v139 offset:1024
	ds_read_b128 v[184:187], v137
	ds_read_b128 v[188:191], v137 offset:1024
	ds_read_b128 v[196:199], v135
	ds_read_b128 v[200:203], v135 offset:1024
	s_add_u32 s0, s12, 0x203f80
	s_addc_u32 s1, s13, 0
	v_lshl_add_u64 v[132:133], s[0:1], 0, v[132:133]
	v_readfirstlane_b32 s12, v148
	s_mov_b32 m0, s12
	global_load_lds_dwordx4 v[132:133], off
	v_lshl_add_u64 v[130:131], s[0:1], 0, v[130:131]
	v_readfirstlane_b32 s0, v150
	s_mov_b32 m0, s0
	global_load_lds_dwordx4 v[130:131], off
	s_barrier
	s_waitcnt lgkmcnt(0)
	s_setprio 1
	v_mfma_f32_16x16x32_bf16 v[126:129], v[152:155], v[168:171], v[126:129]
	v_mfma_f32_16x16x32_bf16 v[122:125], v[160:163], v[168:171], v[122:125]
	v_mfma_f32_16x16x32_bf16 v[118:121], v[152:155], v[176:179], v[118:121]
	v_mfma_f32_16x16x32_bf16 v[114:117], v[160:163], v[176:179], v[114:117]
	v_mfma_f32_16x16x32_bf16 v[102:105], v[152:155], v[196:199], v[102:105]
	v_mfma_f32_16x16x32_bf16 v[98:101], v[160:163], v[196:199], v[98:101]
	v_mfma_f32_16x16x32_bf16 v[126:129], v[156:159], v[172:175], v[126:129]
	v_mfma_f32_16x16x32_bf16 v[122:125], v[164:167], v[172:175], v[122:125]
	v_mfma_f32_16x16x32_bf16 v[118:121], v[156:159], v[180:183], v[118:121]
	v_mfma_f32_16x16x32_bf16 v[114:117], v[164:167], v[180:183], v[114:117]
	v_mfma_f32_16x16x32_bf16 v[110:113], v[152:155], v[184:187], v[110:113]
	v_mfma_f32_16x16x32_bf16 v[106:109], v[160:163], v[184:187], v[106:109]
	v_mfma_f32_16x16x32_bf16 v[102:105], v[156:159], v[200:203], v[102:105]
	v_mfma_f32_16x16x32_bf16 v[98:101], v[164:167], v[200:203], v[98:101]
	v_mfma_f32_16x16x32_bf16 v[130:133], v[156:159], v[188:191], v[110:113]
	v_mfma_f32_16x16x32_bf16 v[148:151], v[164:167], v[188:191], v[106:109]
	s_setprio 0
	s_barrier
	s_nop 0
	ds_read_b128 v[106:109], v147
	ds_read_b128 v[110:113], v147 offset:1024
	ds_read_b128 v[204:207], v147 offset:2048
	ds_read_b128 v[208:211], v147 offset:3072
	s_barrier
	s_waitcnt lgkmcnt(0)
	s_setprio 1
	v_mfma_f32_16x16x32_bf16 v[86:89], v[106:109], v[176:179], v[86:89]
	v_mfma_f32_16x16x32_bf16 v[82:85], v[204:207], v[176:179], v[82:85]
	v_mfma_f32_16x16x32_bf16 v[70:73], v[106:109], v[196:199], v[70:73]
	v_mfma_f32_16x16x32_bf16 v[66:69], v[204:207], v[196:199], v[66:69]
	v_mfma_f32_16x16x32_bf16 v[94:97], v[106:109], v[168:171], v[94:97]
	v_mfma_f32_16x16x32_bf16 v[90:93], v[204:207], v[168:171], v[90:93]
	v_mfma_f32_16x16x32_bf16 v[86:89], v[110:113], v[180:183], v[86:89]
	v_mfma_f32_16x16x32_bf16 v[82:85], v[208:211], v[180:183], v[82:85]
	v_mfma_f32_16x16x32_bf16 v[78:81], v[106:109], v[184:187], v[78:81]
	v_mfma_f32_16x16x32_bf16 v[74:77], v[204:207], v[184:187], v[74:77]
	v_mfma_f32_16x16x32_bf16 v[70:73], v[110:113], v[200:203], v[70:73]
	v_mfma_f32_16x16x32_bf16 v[66:69], v[208:211], v[200:203], v[66:69]
	v_mfma_f32_16x16x32_bf16 v[212:215], v[110:113], v[172:175], v[94:97]
	v_mfma_f32_16x16x32_bf16 v[168:171], v[208:211], v[172:175], v[90:93]
	v_mfma_f32_16x16x32_bf16 v[172:175], v[110:113], v[188:191], v[78:81]
	v_mfma_f32_16x16x32_bf16 v[176:179], v[208:211], v[188:191], v[74:77]
	s_setprio 0
	s_barrier
;   #define LDA(dst,b,h) for(int m=0;m<4;++m)for(int k=0;k<2;++k) \
;     dst[m][k]=*reinterpret_cast<const bf16x8*>((char*)SA(b,h)+lds_byte(wr*64+m*16+fr,k*32+fq*8))
;   #define LDB(dst,b,h) for(int n=0;n<2;++n)for(int k=0;k<2;++k) \
;     dst[n][k]=*reinterpret_cast<const bf16x8*>((char*)SB(b,h)+lds_byte(wc*32+n*16+fr,k*32+fq*8))
;   #define MMA(ai,bj,At,Bt_) do{__builtin_amdgcn_s_setprio(1); \
;     for(int m=0;m<4;++m)for(int n=0;n<2;++n)for(int k=0;k<2;++k) \
;       acc[ai][bj][m][n]=__builtin_amdgcn_mfma_f32_16x16x32_bf16(Bt_[n][k],At[m][k],acc[ai][bj][m][n],0,0,0); \
;     __builtin_amdgcn_s_setprio(0);}while(0)
;   #define WAIT_V(n) asm volatile("s_waitcnt vmcnt(" #n ")":::"memory")
;   #define WAIT_L(n) asm volatile("s_waitcnt lgkmcnt(" #n ")":::"memory")
;   #define BAR __builtin_amdgcn_s_barrier()
; template <bool TWO, class MID> ...
;     ...
;   { LDB(B0,0,0); LDA(At,0,0); STAGE_A(SA(1,1),1,nt-1);
;     BAR; WAIT_L(0); MMA(0,0,At,B0); BAR;
;     LDB(B1,0,1); BAR; WAIT_L(0); MMA(0,1,At,B1); BAR;
;     LDA(At,0,1); WAIT_V(4); BAR; WAIT_L(0); MMA(1,0,At,B0); MMA(1,1,At,B1); BAR; }
;   { LDB(B0,1,0); LDA(At,1,0); WAIT_V(2); BAR; WAIT_L(0); MMA(0,0,At,B0); BAR;
;     LDB(B1,1,1); WAIT_V(0); BAR; WAIT_L(0); MMA(0,1,At,B1); BAR;
	s_nop 0
	ds_read_b128 v[74:77], v141 offset:16384
	ds_read_b128 v[78:81], v141 offset:17408
	ds_read_b128 v[90:93], v139 offset:16384
	ds_read_b128 v[94:97], v139 offset:17408
	ds_read_b128 v[180:183], v137 offset:16384
	ds_read_b128 v[184:187], v137 offset:17408
	ds_read_b128 v[188:191], v135 offset:16384
	ds_read_b128 v[196:199], v135 offset:17408
	s_waitcnt vmcnt(4)
	s_barrier
	s_waitcnt lgkmcnt(0)
	s_setprio 1
	v_mfma_f32_16x16x32_bf16 v[62:65], v[152:155], v[74:77], v[62:65]
	v_mfma_f32_16x16x32_bf16 v[58:61], v[160:163], v[74:77], v[58:61]
	v_mfma_f32_16x16x32_bf16 v[54:57], v[152:155], v[90:93], v[54:57]
	v_mfma_f32_16x16x32_bf16 v[50:53], v[160:163], v[90:93], v[50:53]
	v_mfma_f32_16x16x32_bf16 v[38:41], v[152:155], v[188:191], v[38:41]
	v_mfma_f32_16x16x32_bf16 v[34:37], v[160:163], v[188:191], v[34:37]
	v_mfma_f32_16x16x32_bf16 v[62:65], v[156:159], v[78:81], v[62:65]
	v_mfma_f32_16x16x32_bf16 v[58:61], v[164:167], v[78:81], v[58:61]
	v_mfma_f32_16x16x32_bf16 v[54:57], v[156:159], v[94:97], v[54:57]
	v_mfma_f32_16x16x32_bf16 v[50:53], v[164:167], v[94:97], v[50:53]
	v_mfma_f32_16x16x32_bf16 v[46:49], v[152:155], v[180:183], v[46:49]
	v_mfma_f32_16x16x32_bf16 v[42:45], v[160:163], v[180:183], v[42:45]
	v_mfma_f32_16x16x32_bf16 v[38:41], v[156:159], v[196:199], v[38:41]
	v_mfma_f32_16x16x32_bf16 v[34:37], v[164:167], v[196:199], v[34:37]
	v_mfma_f32_16x16x32_bf16 v[200:203], v[156:159], v[184:187], v[46:49]
	v_mfma_f32_16x16x32_bf16 v[216:219], v[164:167], v[184:187], v[42:45]
	s_setprio 0
	s_setprio 1
	v_mfma_f32_16x16x32_bf16 v[22:25], v[106:109], v[90:93], v[22:25]
	v_mfma_f32_16x16x32_bf16 v[18:21], v[204:207], v[90:93], v[18:21]
	v_mfma_f32_16x16x32_bf16 v[6:9], v[106:109], v[188:191], v[6:9]
	v_mfma_f32_16x16x32_bf16 v[2:5], v[204:207], v[188:191], v[2:5]
	v_mfma_f32_16x16x32_bf16 v[30:33], v[106:109], v[74:77], v[30:33]
	v_mfma_f32_16x16x32_bf16 v[26:29], v[204:207], v[74:77], v[26:29]
	v_mfma_f32_16x16x32_bf16 v[22:25], v[110:113], v[94:97], v[22:25]
	v_mfma_f32_16x16x32_bf16 v[18:21], v[208:211], v[94:97], v[18:21]
	v_mfma_f32_16x16x32_bf16 v[14:17], v[106:109], v[180:183], v[14:17]
	v_mfma_f32_16x16x32_bf16 v[10:13], v[204:207], v[180:183], v[10:13]
	v_mfma_f32_16x16x32_bf16 v[6:9], v[110:113], v[196:199], v[6:9]
	v_mfma_f32_16x16x32_bf16 v[2:5], v[208:211], v[196:199], v[2:5]
	v_mfma_f32_16x16x32_bf16 v[152:155], v[110:113], v[78:81], v[30:33]
	v_mfma_f32_16x16x32_bf16 v[156:159], v[208:211], v[78:81], v[26:29]
	v_mfma_f32_16x16x32_bf16 v[160:163], v[110:113], v[184:187], v[14:17]
	v_mfma_f32_16x16x32_bf16 v[164:167], v[208:211], v[184:187], v[10:13]
	s_setprio 0
	s_barrier
	s_nop 0
	ds_read_b128 v[10:13], v145
	ds_read_b128 v[14:17], v145 offset:1024
	ds_read_b128 v[180:183], v145 offset:2048
	ds_read_b128 v[144:147], v145 offset:3072
	ds_read_b128 v[26:29], v141 offset:32768
	ds_read_b128 v[30:33], v141 offset:33792
	ds_read_b128 v[42:45], v139 offset:32768
	ds_read_b128 v[46:49], v139 offset:33792
	ds_read_b128 v[184:187], v137 offset:32768
	ds_read_b128 v[188:191], v137 offset:33792
	ds_read_b128 v[196:199], v135 offset:32768
	ds_read_b128 v[204:207], v135 offset:33792
	s_waitcnt vmcnt(2)
	s_barrier
	s_waitcnt lgkmcnt(0)
	s_setprio 1
	v_mfma_f32_16x16x32_bf16 v[74:77], v[10:13], v[26:29], v[126:129]
	v_mfma_f32_16x16x32_bf16 v[126:129], v[14:17], v[30:33], v[74:77]
	v_mfma_f32_16x16x32_bf16 v[74:77], v[180:183], v[26:29], v[122:125]
	v_mfma_f32_16x16x32_bf16 v[122:125], v[144:147], v[30:33], v[74:77]
	v_mfma_f32_16x16x32_bf16 v[74:77], v[10:13], v[42:45], v[118:121]
	v_mfma_f32_16x16x32_bf16 v[110:113], v[14:17], v[46:49], v[74:77]
	v_mfma_f32_16x16x32_bf16 v[74:77], v[180:183], v[42:45], v[114:117]
	v_mfma_f32_16x16x32_bf16 v[106:109], v[144:147], v[46:49], v[74:77]
	v_mfma_f32_16x16x32_bf16 v[74:77], v[10:13], v[184:187], v[130:133]
	v_mfma_f32_16x16x32_bf16 v[94:97], v[14:17], v[188:191], v[74:77]
	v_mfma_f32_16x16x32_bf16 v[74:77], v[180:183], v[184:187], v[148:151]
	v_mfma_f32_16x16x32_bf16 v[90:93], v[144:147], v[188:191], v[74:77]
	v_mfma_f32_16x16x32_bf16 v[74:77], v[10:13], v[196:199], v[102:105]
	v_mfma_f32_16x16x32_bf16 v[78:81], v[14:17], v[204:207], v[74:77]
	v_mfma_f32_16x16x32_bf16 v[74:77], v[180:183], v[196:199], v[98:101]
	v_mfma_f32_16x16x32_bf16 v[74:77], v[144:147], v[204:207], v[74:77]
	s_setprio 0
	s_barrier
;   #define LDA(dst,b,h) for(int m=0;m<4;++m)for(int k=0;k<2;++k) \
;     dst[m][k]=*reinterpret_cast<const bf16x8*>((char*)SA(b,h)+lds_byte(wr*64+m*16+fr,k*32+fq*8))
;   #define LDB(dst,b,h) for(int n=0;n<2;++n)for(int k=0;k<2;++k) \
;     dst[n][k]=*reinterpret_cast<const bf16x8*>((char*)SB(b,h)+lds_byte(wc*32+n*16+fr,k*32+fq*8))
;   #define MMA(ai,bj,At,Bt_) do{__builtin_amdgcn_s_setprio(1); \
;     for(int m=0;m<4;++m)for(int n=0;n<2;++n)for(int k=0;k<2;++k) \
;       acc[ai][bj][m][n]=__builtin_amdgcn_mfma_f32_16x16x32_bf16(Bt_[n][k],At[m][k],acc[ai][bj][m][n],0,0,0); \
;     __builtin_amdgcn_s_setprio(0);}while(0)
;   #define WAIT_V(n) asm volatile("s_waitcnt vmcnt(" #n ")":::"memory")
;   #define WAIT_L(n) asm volatile("s_waitcnt lgkmcnt(" #n ")":::"memory")
;   #define BAR __builtin_amdgcn_s_barrier()
; template <bool TWO, class MID> ...
;     ...
;     LDA(At,0,1); WAIT_V(4); BAR; WAIT_L(0); MMA(1,0,At,B0); MMA(1,1,At,B1); BAR; }
;   { LDB(B0,1,0); LDA(At,1,0); WAIT_V(2); BAR; WAIT_L(0); MMA(0,0,At,B0); BAR;
;     LDB(B1,1,1); WAIT_V(0); BAR; WAIT_L(0); MMA(0,1,At,B1); BAR;
;     LDA(At,1,1); BAR; WAIT_L(0); MMA(1,0,At,B0); MMA(1,1,At,B1); BAR; }
;   if(wr==0)BAR;
	ds_read_b128 v[130:133], v143
	ds_read_b128 v[148:151], v143 offset:1024
	ds_read_b128 v[208:211], v143 offset:2048
	ds_read_b128 v[220:223], v143 offset:3072
	s_waitcnt vmcnt(0)
	s_barrier
	s_waitcnt lgkmcnt(0)
	s_setprio 1
	v_mfma_f32_16x16x32_bf16 v[98:101], v[130:133], v[26:29], v[212:215]
	v_mfma_f32_16x16x32_bf16 v[26:29], v[208:211], v[26:29], v[168:171]
	v_mfma_f32_16x16x32_bf16 v[114:117], v[220:223], v[30:33], v[26:29]
	v_mfma_f32_16x16x32_bf16 v[26:29], v[130:133], v[42:45], v[86:89]
	v_mfma_f32_16x16x32_bf16 v[102:105], v[148:151], v[46:49], v[26:29]
	v_mfma_f32_16x16x32_bf16 v[26:29], v[208:211], v[42:45], v[82:85]
	v_mfma_f32_16x16x32_bf16 v[118:121], v[148:151], v[30:33], v[98:101]
	v_mfma_f32_16x16x32_bf16 v[98:101], v[220:223], v[46:49], v[26:29]
	v_mfma_f32_16x16x32_bf16 v[26:29], v[130:133], v[184:187], v[172:175]
	v_mfma_f32_16x16x32_bf16 v[86:89], v[148:151], v[188:191], v[26:29]
	v_mfma_f32_16x16x32_bf16 v[26:29], v[208:211], v[184:187], v[176:179]
	v_mfma_f32_16x16x32_bf16 v[82:85], v[220:223], v[188:191], v[26:29]
	v_mfma_f32_16x16x32_bf16 v[26:29], v[130:133], v[196:199], v[70:73]
	v_mfma_f32_16x16x32_bf16 v[70:73], v[148:151], v[204:207], v[26:29]
	v_mfma_f32_16x16x32_bf16 v[26:29], v[208:211], v[196:199], v[66:69]
	v_mfma_f32_16x16x32_bf16 v[66:69], v[220:223], v[204:207], v[26:29]
	s_setprio 0
	s_barrier
	ds_read_b128 v[168:171], v141 offset:49152
	ds_read_b128 v[140:143], v141 offset:50176
	ds_read_b128 v[172:175], v139 offset:49152
	ds_read_b128 v[176:179], v139 offset:50176
	ds_read_b128 v[184:187], v137 offset:49152
	ds_read_b128 v[136:139], v137 offset:50176
	ds_read_b128 v[188:191], v135 offset:49152
	ds_read_b128 v[196:199], v135 offset:50176
	s_barrier
	s_waitcnt lgkmcnt(0)
	s_setprio 1
	v_mfma_f32_16x16x32_bf16 v[26:29], v[10:13], v[168:171], v[62:65]
	v_mfma_f32_16x16x32_bf16 v[62:65], v[14:17], v[140:143], v[26:29]
	v_mfma_f32_16x16x32_bf16 v[26:29], v[180:183], v[168:171], v[58:61]
	v_mfma_f32_16x16x32_bf16 v[58:61], v[144:147], v[140:143], v[26:29]
	v_mfma_f32_16x16x32_bf16 v[26:29], v[10:13], v[172:175], v[54:57]
	v_mfma_f32_16x16x32_bf16 v[46:49], v[14:17], v[176:179], v[26:29]
	v_mfma_f32_16x16x32_bf16 v[26:29], v[180:183], v[172:175], v[50:53]
	v_mfma_f32_16x16x32_bf16 v[42:45], v[144:147], v[176:179], v[26:29]
	v_mfma_f32_16x16x32_bf16 v[26:29], v[10:13], v[184:187], v[200:203]
	v_mfma_f32_16x16x32_bf16 v[10:13], v[10:13], v[188:191], v[38:41]
	v_mfma_f32_16x16x32_bf16 v[30:33], v[14:17], v[136:139], v[26:29]
	v_mfma_f32_16x16x32_bf16 v[26:29], v[180:183], v[184:187], v[216:219]
	v_mfma_f32_16x16x32_bf16 v[14:17], v[14:17], v[196:199], v[10:13]
	v_mfma_f32_16x16x32_bf16 v[10:13], v[180:183], v[188:191], v[34:37]
	v_mfma_f32_16x16x32_bf16 v[26:29], v[144:147], v[136:139], v[26:29]
	v_mfma_f32_16x16x32_bf16 v[10:13], v[144:147], v[196:199], v[10:13]
	s_setprio 0
	s_setprio 1
	v_mfma_f32_16x16x32_bf16 v[34:37], v[130:133], v[168:171], v[152:155]
	v_mfma_f32_16x16x32_bf16 v[54:57], v[148:151], v[140:143], v[34:37]
	v_mfma_f32_16x16x32_bf16 v[34:37], v[208:211], v[168:171], v[156:159]
	v_mfma_f32_16x16x32_bf16 v[18:21], v[208:211], v[172:175], v[18:21]
	v_mfma_f32_16x16x32_bf16 v[50:53], v[220:223], v[140:143], v[34:37]
	v_mfma_f32_16x16x32_bf16 v[22:25], v[130:133], v[172:175], v[22:25]
	v_mfma_f32_16x16x32_bf16 v[34:37], v[220:223], v[176:179], v[18:21]
	v_mfma_f32_16x16x32_bf16 v[18:21], v[130:133], v[184:187], v[160:163]
	v_mfma_f32_16x16x32_bf16 v[38:41], v[148:151], v[176:179], v[22:25]
	v_mfma_f32_16x16x32_bf16 v[22:25], v[148:151], v[136:139], v[18:21]
	v_mfma_f32_16x16x32_bf16 v[18:21], v[208:211], v[184:187], v[164:167]
	v_mfma_f32_16x16x32_bf16 v[6:9], v[130:133], v[188:191], v[6:9]
	v_mfma_f32_16x16x32_bf16 v[2:5], v[208:211], v[188:191], v[2:5]
	v_mfma_f32_16x16x32_bf16 v[18:21], v[220:223], v[136:139], v[18:21]
	v_mfma_f32_16x16x32_bf16 v[6:9], v[148:151], v[196:199], v[6:9]
	v_mfma_f32_16x16x32_bf16 v[2:5], v[220:223], v[196:199], v[2:5]
	s_setprio 0
	v_cmp_gt_u32_e32 vcc, s30, v1
	s_barrier
	s_and_saveexec_b64 s[0:1], vcc
	s_cbranch_execz .LBB0_623
	s_barrier
